# normalised-activation (HN) stores written through (sc1); the three grid barriers that follow them skip the L2 write-back
# speedup vs baseline: 1.0100x; 1.0100x over previous
.Lgs_noreset:
	s_lshl_b32 s46, s2, 3
	v_ashrrev_i32_e32 v0, 6, v2
	v_add_u32_e32 v3, s46, v0
	s_movk_i32 s3, 0x3000
	s_lshl_b32 s44, s42, 3
	v_cmp_gt_i32_e32 vcc, s3, v3
	v_mbcnt_lo_u32_b32 v135, -1, 0
	s_load_dwordx2 s[52:53], s[0:1], 0xe8
	v_mov_b32_e32 v231, 0x358637bd
	v_lshlrev_b32_e32 v230, 3, v222
	v_xor_b32_e32 v223, 32, v222
	v_xor_b32_e32 v224, 16, v222
	v_xor_b32_e32 v225, 8, v222
	v_xor_b32_e32 v226, 4, v222
	v_xor_b32_e32 v227, 2, v222
	v_xor_b32_e32 v228, 1, v222
	v_lshlrev_b32_e32 v223, 2, v223
	v_lshlrev_b32_e32 v224, 2, v224
	v_lshlrev_b32_e32 v225, 2, v225
	v_lshlrev_b32_e32 v226, 2, v226
	v_lshlrev_b32_e32 v227, 2, v227
	v_lshlrev_b32_e32 v228, 2, v228
	s_waitcnt lgkmcnt(0)
	s_add_u32 s58, s52, 0x780000
	s_addc_u32 s59, s53, 0
	s_add_u32 s60, s58, 0x0
	s_addc_u32 s61, s59, 0
	global_load_dwordx4 v[0:3], v229, s[60:61]
	global_load_dwordx4 v[4:7], v229, s[60:61] offset:1024
	global_load_dwordx4 v[8:11], v229, s[60:61] offset:2048
	global_load_dwordx4 v[12:15], v229, s[60:61] offset:3072
	s_add_u32 s60, s60, 0x1000
	s_addc_u32 s61, s61, 0
	global_load_dwordx4 v[16:19], v229, s[60:61]
	global_load_dwordx4 v[20:23], v229, s[60:61] offset:1024
	global_load_dwordx4 v[24:27], v229, s[60:61] offset:2048
	global_load_dwordx4 v[28:31], v229, s[60:61] offset:3072
	s_add_u32 s60, s58, 0x6000
	s_addc_u32 s61, s59, 0
	global_load_dwordx4 v[32:35], v229, s[60:61]
	global_load_dwordx4 v[36:39], v229, s[60:61] offset:1024
	global_load_dwordx4 v[40:43], v229, s[60:61] offset:2048
	global_load_dwordx4 v[44:47], v229, s[60:61] offset:3072
	s_add_u32 s60, s60, 0x1000
	s_addc_u32 s61, s61, 0
	global_load_dwordx4 v[48:51], v229, s[60:61]
	global_load_dwordx4 v[52:55], v229, s[60:61] offset:1024
	global_load_dwordx4 v[56:59], v229, s[60:61] offset:2048
	global_load_dwordx4 v[60:63], v229, s[60:61] offset:3072
	s_waitcnt vmcnt(36)
	v_mul_f32_e32 v210, v96, v96
	v_fmac_f32_e32 v210, v97, v97
	v_fmac_f32_e32 v210, v98, v98
	v_fmac_f32_e32 v210, v99, v99
	v_fmac_f32_e32 v210, v100, v100
	v_fmac_f32_e32 v210, v101, v101
	v_fmac_f32_e32 v210, v102, v102
	v_fmac_f32_e32 v210, v103, v103
	v_fmac_f32_e32 v210, v104, v104
	v_fmac_f32_e32 v210, v105, v105
	v_fmac_f32_e32 v210, v106, v106
	v_fmac_f32_e32 v210, v107, v107
	v_fmac_f32_e32 v210, v108, v108
	v_fmac_f32_e32 v210, v109, v109
	v_fmac_f32_e32 v210, v110, v110
	v_fmac_f32_e32 v210, v111, v111
	s_waitcnt vmcnt(32)
	v_mul_f32_e32 v212, v112, v112
	v_fmac_f32_e32 v212, v113, v113
	v_fmac_f32_e32 v212, v114, v114
	v_fmac_f32_e32 v212, v115, v115
	v_fmac_f32_e32 v212, v116, v116
	v_fmac_f32_e32 v212, v117, v117
	v_fmac_f32_e32 v212, v118, v118
	v_fmac_f32_e32 v212, v119, v119
	v_fmac_f32_e32 v212, v120, v120
	v_fmac_f32_e32 v212, v121, v121
	v_fmac_f32_e32 v212, v122, v122
	v_fmac_f32_e32 v212, v123, v123
	v_fmac_f32_e32 v212, v124, v124
	v_fmac_f32_e32 v212, v125, v125
	v_fmac_f32_e32 v212, v126, v126
	v_fmac_f32_e32 v212, v127, v127
	s_waitcnt vmcnt(28)
	v_mul_f32_e32 v214, v136, v136
	v_fmac_f32_e32 v214, v137, v137
	v_fmac_f32_e32 v214, v138, v138
	v_fmac_f32_e32 v214, v139, v139
	v_fmac_f32_e32 v214, v140, v140
	v_fmac_f32_e32 v214, v141, v141
	v_fmac_f32_e32 v214, v142, v142
	v_fmac_f32_e32 v214, v143, v143
	v_fmac_f32_e32 v214, v144, v144
	v_fmac_f32_e32 v214, v145, v145
	v_fmac_f32_e32 v214, v146, v146
	v_fmac_f32_e32 v214, v147, v147
	v_fmac_f32_e32 v214, v148, v148
	v_fmac_f32_e32 v214, v149, v149
	v_fmac_f32_e32 v214, v150, v150
	v_fmac_f32_e32 v214, v151, v151
	s_waitcnt vmcnt(24)
	v_mul_f32_e32 v216, v152, v152
	v_fmac_f32_e32 v216, v153, v153
	v_fmac_f32_e32 v216, v154, v154
	v_fmac_f32_e32 v216, v155, v155
	v_fmac_f32_e32 v216, v156, v156
	v_fmac_f32_e32 v216, v157, v157
	v_fmac_f32_e32 v216, v158, v158
	v_fmac_f32_e32 v216, v159, v159
	v_fmac_f32_e32 v216, v160, v160
	v_fmac_f32_e32 v216, v161, v161
	v_fmac_f32_e32 v216, v162, v162
	v_fmac_f32_e32 v216, v163, v163
	v_fmac_f32_e32 v216, v164, v164
	v_fmac_f32_e32 v216, v165, v165
	v_fmac_f32_e32 v216, v166, v166
	v_fmac_f32_e32 v216, v167, v167
	s_waitcnt vmcnt(20)
	v_mul_f32_e32 v218, v178, v178
	v_fmac_f32_e32 v218, v179, v179
	v_fmac_f32_e32 v218, v180, v180
	v_fmac_f32_e32 v218, v181, v181
	v_fmac_f32_e32 v218, v182, v182
	v_fmac_f32_e32 v218, v183, v183
	v_fmac_f32_e32 v218, v184, v184
	v_fmac_f32_e32 v218, v185, v185
	v_fmac_f32_e32 v218, v186, v186
	v_fmac_f32_e32 v218, v187, v187
	v_fmac_f32_e32 v218, v188, v188
	v_fmac_f32_e32 v218, v189, v189
	v_fmac_f32_e32 v218, v190, v190
	v_fmac_f32_e32 v218, v191, v191
	v_fmac_f32_e32 v218, v192, v192
	v_fmac_f32_e32 v218, v193, v193
	s_waitcnt vmcnt(16)
	v_mul_f32_e32 v220, v194, v194
	v_fmac_f32_e32 v220, v195, v195
	v_fmac_f32_e32 v220, v196, v196
	v_fmac_f32_e32 v220, v197, v197
	v_fmac_f32_e32 v220, v198, v198
	v_fmac_f32_e32 v220, v199, v199
	v_fmac_f32_e32 v220, v200, v200
	v_fmac_f32_e32 v220, v201, v201
	v_fmac_f32_e32 v220, v202, v202
	v_fmac_f32_e32 v220, v203, v203
	v_fmac_f32_e32 v220, v204, v204
	v_fmac_f32_e32 v220, v205, v205
	v_fmac_f32_e32 v220, v206, v206
	v_fmac_f32_e32 v220, v207, v207
	v_fmac_f32_e32 v220, v208, v208
	v_fmac_f32_e32 v220, v209, v209
	ds_bpermute_b32 v211, v223, v210
	ds_bpermute_b32 v213, v223, v212
	ds_bpermute_b32 v215, v223, v214
	ds_bpermute_b32 v217, v223, v216
	ds_bpermute_b32 v219, v223, v218
	ds_bpermute_b32 v221, v223, v220
	s_waitcnt lgkmcnt(5)
	v_add_f32_e32 v210, v210, v211
	s_waitcnt lgkmcnt(4)
	v_add_f32_e32 v212, v212, v213
	s_waitcnt lgkmcnt(3)
	v_add_f32_e32 v214, v214, v215
	s_waitcnt lgkmcnt(2)
	v_add_f32_e32 v216, v216, v217
	s_waitcnt lgkmcnt(1)
	v_add_f32_e32 v218, v218, v219
	s_waitcnt lgkmcnt(0)
	v_add_f32_e32 v220, v220, v221
	ds_bpermute_b32 v211, v224, v210
	ds_bpermute_b32 v213, v224, v212
	ds_bpermute_b32 v215, v224, v214
	ds_bpermute_b32 v217, v224, v216
	ds_bpermute_b32 v219, v224, v218
	ds_bpermute_b32 v221, v224, v220
	s_waitcnt lgkmcnt(5)
	v_add_f32_e32 v210, v210, v211
	s_waitcnt lgkmcnt(4)
	v_add_f32_e32 v212, v212, v213
	s_waitcnt lgkmcnt(3)
	v_add_f32_e32 v214, v214, v215
	s_waitcnt lgkmcnt(2)
	v_add_f32_e32 v216, v216, v217
	s_waitcnt lgkmcnt(1)
	v_add_f32_e32 v218, v218, v219
	s_waitcnt lgkmcnt(0)
	v_add_f32_e32 v220, v220, v221
	ds_bpermute_b32 v211, v225, v210
	ds_bpermute_b32 v213, v225, v212
	ds_bpermute_b32 v215, v225, v214
	ds_bpermute_b32 v217, v225, v216
	ds_bpermute_b32 v219, v225, v218
	ds_bpermute_b32 v221, v225, v220
	s_waitcnt lgkmcnt(5)
	v_add_f32_e32 v210, v210, v211
	s_waitcnt lgkmcnt(4)
	v_add_f32_e32 v212, v212, v213
	s_waitcnt lgkmcnt(3)
	v_add_f32_e32 v214, v214, v215
	s_waitcnt lgkmcnt(2)
	v_add_f32_e32 v216, v216, v217
	s_waitcnt lgkmcnt(1)
	v_add_f32_e32 v218, v218, v219
	s_waitcnt lgkmcnt(0)
	v_add_f32_e32 v220, v220, v221
	ds_bpermute_b32 v211, v226, v210
	ds_bpermute_b32 v213, v226, v212
	ds_bpermute_b32 v215, v226, v214
	ds_bpermute_b32 v217, v226, v216
	ds_bpermute_b32 v219, v226, v218
	ds_bpermute_b32 v221, v226, v220
	s_waitcnt lgkmcnt(5)
	v_add_f32_e32 v210, v210, v211
	s_waitcnt lgkmcnt(4)
	v_add_f32_e32 v212, v212, v213
	s_waitcnt lgkmcnt(3)
	v_add_f32_e32 v214, v214, v215
	s_waitcnt lgkmcnt(2)
	v_add_f32_e32 v216, v216, v217
	s_waitcnt lgkmcnt(1)
	v_add_f32_e32 v218, v218, v219
	s_waitcnt lgkmcnt(0)
	v_add_f32_e32 v220, v220, v221
	ds_bpermute_b32 v211, v227, v210
	ds_bpermute_b32 v213, v227, v212
	ds_bpermute_b32 v215, v227, v214
	ds_bpermute_b32 v217, v227, v216
	ds_bpermute_b32 v219, v227, v218
	ds_bpermute_b32 v221, v227, v220
	s_waitcnt lgkmcnt(5)
	v_add_f32_e32 v210, v210, v211
	s_waitcnt lgkmcnt(4)
	v_add_f32_e32 v212, v212, v213
	s_waitcnt lgkmcnt(3)
	v_add_f32_e32 v214, v214, v215
	s_waitcnt lgkmcnt(2)
	v_add_f32_e32 v216, v216, v217
	s_waitcnt lgkmcnt(1)
	v_add_f32_e32 v218, v218, v219
	s_waitcnt lgkmcnt(0)
	v_add_f32_e32 v220, v220, v221
	ds_bpermute_b32 v211, v228, v210
	ds_bpermute_b32 v213, v228, v212
	ds_bpermute_b32 v215, v228, v214
	ds_bpermute_b32 v217, v228, v216
	ds_bpermute_b32 v219, v228, v218
	ds_bpermute_b32 v221, v228, v220
	s_waitcnt lgkmcnt(5)
	v_add_f32_e32 v210, v210, v211
	s_waitcnt lgkmcnt(4)
	v_add_f32_e32 v212, v212, v213
	s_waitcnt lgkmcnt(3)
	v_add_f32_e32 v214, v214, v215
	s_waitcnt lgkmcnt(2)
	v_add_f32_e32 v216, v216, v217
	s_waitcnt lgkmcnt(1)
	v_add_f32_e32 v218, v218, v219
	s_waitcnt lgkmcnt(0)
	v_add_f32_e32 v220, v220, v221
	v_fmamk_f32 v210, v210, 0x3a800000, v231
	v_fmamk_f32 v212, v212, 0x3a800000, v231
	v_fmamk_f32 v214, v214, 0x3a800000, v231
	v_fmamk_f32 v216, v216, 0x3a800000, v231
	v_fmamk_f32 v218, v218, 0x3a800000, v231
	v_fmamk_f32 v220, v220, 0x3a800000, v231
	v_rsq_f32_e32 v210, v210
	v_rsq_f32_e32 v212, v212
	v_rsq_f32_e32 v214, v214
	v_rsq_f32_e32 v216, v216
	v_rsq_f32_e32 v218, v218
	v_rsq_f32_e32 v220, v220
	s_lshl_b32 s67, s66, 11
	s_add_u32 s56, s52, 0x2ebc000
	s_addc_u32 s57, s53, 0
	s_add_u32 s56, s56, s67
	s_addc_u32 s57, s57, 0
	s_waitcnt vmcnt(0)
	v_pk_mul_f32 v[96:97], v[96:97], v[210:211] op_sel_hi:[1,0]
	v_pk_mul_f32 v[98:99], v[98:99], v[210:211] op_sel_hi:[1,0]
	v_pk_fma_f32 v[96:97], v[96:97], v[0:1], v[16:17]
	v_pk_fma_f32 v[98:99], v[98:99], v[2:3], v[18:19]
	v_cvt_pk_bf16_f32 v96, v96, v97
	v_cvt_pk_bf16_f32 v97, v98, v99
	global_store_dwordx2 v230, v[96:97], s[56:57] sc1
	v_pk_mul_f32 v[100:101], v[100:101], v[210:211] op_sel_hi:[1,0]
	v_pk_mul_f32 v[102:103], v[102:103], v[210:211] op_sel_hi:[1,0]
	v_pk_fma_f32 v[100:101], v[100:101], v[4:5], v[20:21]
	v_pk_fma_f32 v[102:103], v[102:103], v[6:7], v[22:23]
	v_cvt_pk_bf16_f32 v100, v100, v101
	v_cvt_pk_bf16_f32 v101, v102, v103
	global_store_dwordx2 v230, v[100:101], s[56:57] offset:512 sc1
	v_pk_mul_f32 v[104:105], v[104:105], v[210:211] op_sel_hi:[1,0]
	v_pk_mul_f32 v[106:107], v[106:107], v[210:211] op_sel_hi:[1,0]
	v_pk_fma_f32 v[104:105], v[104:105], v[8:9], v[24:25]
	v_pk_fma_f32 v[106:107], v[106:107], v[10:11], v[26:27]
	v_cvt_pk_bf16_f32 v104, v104, v105
	v_cvt_pk_bf16_f32 v105, v106, v107
	global_store_dwordx2 v230, v[104:105], s[56:57] offset:1024 sc1
	v_pk_mul_f32 v[108:109], v[108:109], v[210:211] op_sel_hi:[1,0]
	v_pk_mul_f32 v[110:111], v[110:111], v[210:211] op_sel_hi:[1,0]
	v_pk_fma_f32 v[108:109], v[108:109], v[12:13], v[28:29]
	v_pk_fma_f32 v[110:111], v[110:111], v[14:15], v[30:31]
	v_cvt_pk_bf16_f32 v108, v108, v109
	v_cvt_pk_bf16_f32 v109, v110, v111
	global_store_dwordx2 v230, v[108:109], s[56:57] offset:1536 sc1
	s_add_u32 s56, s56, 0x400000
	s_addc_u32 s57, s57, 0
	v_pk_mul_f32 v[112:113], v[112:113], v[212:213] op_sel_hi:[1,0]
	v_pk_mul_f32 v[114:115], v[114:115], v[212:213] op_sel_hi:[1,0]
	v_pk_fma_f32 v[112:113], v[112:113], v[0:1], v[16:17]
	v_pk_fma_f32 v[114:115], v[114:115], v[2:3], v[18:19]
	v_cvt_pk_bf16_f32 v112, v112, v113
	v_cvt_pk_bf16_f32 v113, v114, v115
	global_store_dwordx2 v230, v[112:113], s[56:57] sc1
	v_pk_mul_f32 v[116:117], v[116:117], v[212:213] op_sel_hi:[1,0]
	v_pk_mul_f32 v[118:119], v[118:119], v[212:213] op_sel_hi:[1,0]
	v_pk_fma_f32 v[116:117], v[116:117], v[4:5], v[20:21]
	v_pk_fma_f32 v[118:119], v[118:119], v[6:7], v[22:23]
	v_cvt_pk_bf16_f32 v116, v116, v117
	v_cvt_pk_bf16_f32 v117, v118, v119
	global_store_dwordx2 v230, v[116:117], s[56:57] offset:512 sc1
	v_pk_mul_f32 v[120:121], v[120:121], v[212:213] op_sel_hi:[1,0]
	v_pk_mul_f32 v[122:123], v[122:123], v[212:213] op_sel_hi:[1,0]
	v_pk_fma_f32 v[120:121], v[120:121], v[8:9], v[24:25]
	v_pk_fma_f32 v[122:123], v[122:123], v[10:11], v[26:27]
	v_cvt_pk_bf16_f32 v120, v120, v121
	v_cvt_pk_bf16_f32 v121, v122, v123
	global_store_dwordx2 v230, v[120:121], s[56:57] offset:1024 sc1
	v_pk_mul_f32 v[124:125], v[124:125], v[212:213] op_sel_hi:[1,0]
	v_pk_mul_f32 v[126:127], v[126:127], v[212:213] op_sel_hi:[1,0]
	v_pk_fma_f32 v[124:125], v[124:125], v[12:13], v[28:29]
	v_pk_fma_f32 v[126:127], v[126:127], v[14:15], v[30:31]
	v_cvt_pk_bf16_f32 v124, v124, v125
	v_cvt_pk_bf16_f32 v125, v126, v127
	global_store_dwordx2 v230, v[124:125], s[56:57] offset:1536 sc1
	s_add_u32 s56, s56, 0x400000
	s_addc_u32 s57, s57, 0
	v_pk_mul_f32 v[136:137], v[136:137], v[214:215] op_sel_hi:[1,0]
	v_pk_mul_f32 v[138:139], v[138:139], v[214:215] op_sel_hi:[1,0]
	v_pk_fma_f32 v[136:137], v[136:137], v[32:33], v[48:49]
	v_pk_fma_f32 v[138:139], v[138:139], v[34:35], v[50:51]
	v_cvt_pk_bf16_f32 v136, v136, v137
	v_cvt_pk_bf16_f32 v137, v138, v139
	global_store_dwordx2 v230, v[136:137], s[56:57] sc1
	v_pk_mul_f32 v[140:141], v[140:141], v[214:215] op_sel_hi:[1,0]
	v_pk_mul_f32 v[142:143], v[142:143], v[214:215] op_sel_hi:[1,0]
	v_pk_fma_f32 v[140:141], v[140:141], v[36:37], v[52:53]
	v_pk_fma_f32 v[142:143], v[142:143], v[38:39], v[54:55]
	v_cvt_pk_bf16_f32 v140, v140, v141
	v_cvt_pk_bf16_f32 v141, v142, v143
	global_store_dwordx2 v230, v[140:141], s[56:57] offset:512 sc1
	v_pk_mul_f32 v[144:145], v[144:145], v[214:215] op_sel_hi:[1,0]
	v_pk_mul_f32 v[146:147], v[146:147], v[214:215] op_sel_hi:[1,0]
	v_pk_fma_f32 v[144:145], v[144:145], v[40:41], v[56:57]
	v_pk_fma_f32 v[146:147], v[146:147], v[42:43], v[58:59]
	v_cvt_pk_bf16_f32 v144, v144, v145
	v_cvt_pk_bf16_f32 v145, v146, v147
	global_store_dwordx2 v230, v[144:145], s[56:57] offset:1024 sc1
	v_pk_mul_f32 v[148:149], v[148:149], v[214:215] op_sel_hi:[1,0]
	v_pk_mul_f32 v[150:151], v[150:151], v[214:215] op_sel_hi:[1,0]
	v_pk_fma_f32 v[148:149], v[148:149], v[44:45], v[60:61]
	v_pk_fma_f32 v[150:151], v[150:151], v[46:47], v[62:63]
	v_cvt_pk_bf16_f32 v148, v148, v149
	v_cvt_pk_bf16_f32 v149, v150, v151
	global_store_dwordx2 v230, v[148:149], s[56:57] offset:1536 sc1
	s_add_u32 s56, s56, 0x400000
	s_addc_u32 s57, s57, 0
	s_add_u32 s60, s58, 0xc000
	s_addc_u32 s61, s59, 0
	global_load_dwordx4 v[0:3], v229, s[60:61]
	global_load_dwordx4 v[4:7], v229, s[60:61] offset:1024
	global_load_dwordx4 v[8:11], v229, s[60:61] offset:2048
	global_load_dwordx4 v[12:15], v229, s[60:61] offset:3072
	s_add_u32 s60, s60, 0x1000
	s_addc_u32 s61, s61, 0
	global_load_dwordx4 v[16:19], v229, s[60:61]
	global_load_dwordx4 v[20:23], v229, s[60:61] offset:1024
	global_load_dwordx4 v[24:27], v229, s[60:61] offset:2048
	global_load_dwordx4 v[28:31], v229, s[60:61] offset:3072
	s_add_u32 s60, s58, 0x12000
	s_addc_u32 s61, s59, 0
	global_load_dwordx4 v[32:35], v229, s[60:61]
	global_load_dwordx4 v[36:39], v229, s[60:61] offset:1024
	global_load_dwordx4 v[40:43], v229, s[60:61] offset:2048
	global_load_dwordx4 v[44:47], v229, s[60:61] offset:3072
	s_add_u32 s60, s60, 0x1000
	s_addc_u32 s61, s61, 0
	global_load_dwordx4 v[48:51], v229, s[60:61]
	global_load_dwordx4 v[52:55], v229, s[60:61] offset:1024
	global_load_dwordx4 v[56:59], v229, s[60:61] offset:2048
	global_load_dwordx4 v[60:63], v229, s[60:61] offset:3072
	s_add_u32 s60, s58, 0x18000
	s_addc_u32 s61, s59, 0
	global_load_dwordx4 v[64:67], v229, s[60:61]
	global_load_dwordx4 v[68:71], v229, s[60:61] offset:1024
	global_load_dwordx4 v[72:75], v229, s[60:61] offset:2048
	global_load_dwordx4 v[76:79], v229, s[60:61] offset:3072
	s_add_u32 s60, s60, 0x1000
	s_addc_u32 s61, s61, 0
	global_load_dwordx4 v[80:83], v229, s[60:61]
	global_load_dwordx4 v[84:87], v229, s[60:61] offset:1024
	global_load_dwordx4 v[88:91], v229, s[60:61] offset:2048
	global_load_dwordx4 v[92:95], v229, s[60:61] offset:3072
	s_waitcnt vmcnt(16)
	v_pk_mul_f32 v[152:153], v[152:153], v[216:217] op_sel_hi:[1,0]
	v_pk_mul_f32 v[154:155], v[154:155], v[216:217] op_sel_hi:[1,0]
	v_pk_fma_f32 v[152:153], v[152:153], v[0:1], v[16:17]
	v_pk_fma_f32 v[154:155], v[154:155], v[2:3], v[18:19]
	v_cvt_pk_bf16_f32 v152, v152, v153
	v_cvt_pk_bf16_f32 v153, v154, v155
	global_store_dwordx2 v230, v[152:153], s[56:57] sc1
	v_pk_mul_f32 v[156:157], v[156:157], v[216:217] op_sel_hi:[1,0]
	v_pk_mul_f32 v[158:159], v[158:159], v[216:217] op_sel_hi:[1,0]
	v_pk_fma_f32 v[156:157], v[156:157], v[4:5], v[20:21]
	v_pk_fma_f32 v[158:159], v[158:159], v[6:7], v[22:23]
	v_cvt_pk_bf16_f32 v156, v156, v157
	v_cvt_pk_bf16_f32 v157, v158, v159
	global_store_dwordx2 v230, v[156:157], s[56:57] offset:512 sc1
	v_pk_mul_f32 v[160:161], v[160:161], v[216:217] op_sel_hi:[1,0]
	v_pk_mul_f32 v[162:163], v[162:163], v[216:217] op_sel_hi:[1,0]
	v_pk_fma_f32 v[160:161], v[160:161], v[8:9], v[24:25]
	v_pk_fma_f32 v[162:163], v[162:163], v[10:11], v[26:27]
	v_cvt_pk_bf16_f32 v160, v160, v161
	v_cvt_pk_bf16_f32 v161, v162, v163
	global_store_dwordx2 v230, v[160:161], s[56:57] offset:1024 sc1
	v_pk_mul_f32 v[164:165], v[164:165], v[216:217] op_sel_hi:[1,0]
	v_pk_mul_f32 v[166:167], v[166:167], v[216:217] op_sel_hi:[1,0]
	v_pk_fma_f32 v[164:165], v[164:165], v[12:13], v[28:29]
	v_pk_fma_f32 v[166:167], v[166:167], v[14:15], v[30:31]
	v_cvt_pk_bf16_f32 v164, v164, v165
	v_cvt_pk_bf16_f32 v165, v166, v167
	global_store_dwordx2 v230, v[164:165], s[56:57] offset:1536 sc1
	s_add_u32 s56, s56, 0x400000
	s_addc_u32 s57, s57, 0
	s_waitcnt vmcnt(12)
	v_pk_mul_f32 v[178:179], v[178:179], v[218:219] op_sel_hi:[1,0]
	v_pk_mul_f32 v[180:181], v[180:181], v[218:219] op_sel_hi:[1,0]
	v_pk_fma_f32 v[178:179], v[178:179], v[32:33], v[48:49]
	v_pk_fma_f32 v[180:181], v[180:181], v[34:35], v[50:51]
	v_cvt_pk_bf16_f32 v178, v178, v179
	v_cvt_pk_bf16_f32 v179, v180, v181
	global_store_dwordx2 v230, v[178:179], s[56:57] sc1
	v_pk_mul_f32 v[182:183], v[182:183], v[218:219] op_sel_hi:[1,0]
	v_pk_mul_f32 v[184:185], v[184:185], v[218:219] op_sel_hi:[1,0]
	v_pk_fma_f32 v[182:183], v[182:183], v[36:37], v[52:53]
	v_pk_fma_f32 v[184:185], v[184:185], v[38:39], v[54:55]
	v_cvt_pk_bf16_f32 v182, v182, v183
	v_cvt_pk_bf16_f32 v183, v184, v185
	global_store_dwordx2 v230, v[182:183], s[56:57] offset:512 sc1
	v_pk_mul_f32 v[186:187], v[186:187], v[218:219] op_sel_hi:[1,0]
	v_pk_mul_f32 v[188:189], v[188:189], v[218:219] op_sel_hi:[1,0]
	v_pk_fma_f32 v[186:187], v[186:187], v[40:41], v[56:57]
	v_pk_fma_f32 v[188:189], v[188:189], v[42:43], v[58:59]
	v_cvt_pk_bf16_f32 v186, v186, v187
	v_cvt_pk_bf16_f32 v187, v188, v189
	global_store_dwordx2 v230, v[186:187], s[56:57] offset:1024 sc1
	v_pk_mul_f32 v[190:191], v[190:191], v[218:219] op_sel_hi:[1,0]
	v_pk_mul_f32 v[192:193], v[192:193], v[218:219] op_sel_hi:[1,0]
	v_pk_fma_f32 v[190:191], v[190:191], v[44:45], v[60:61]
	v_pk_fma_f32 v[192:193], v[192:193], v[46:47], v[62:63]
	v_cvt_pk_bf16_f32 v190, v190, v191
	v_cvt_pk_bf16_f32 v191, v192, v193
	global_store_dwordx2 v230, v[190:191], s[56:57] offset:1536 sc1
	s_add_u32 s56, s56, 0x400000
	s_addc_u32 s57, s57, 0
	s_waitcnt vmcnt(8)
	v_pk_mul_f32 v[194:195], v[194:195], v[220:221] op_sel_hi:[1,0]
	v_pk_mul_f32 v[196:197], v[196:197], v[220:221] op_sel_hi:[1,0]
	v_pk_fma_f32 v[194:195], v[194:195], v[64:65], v[80:81]
	v_pk_fma_f32 v[196:197], v[196:197], v[66:67], v[82:83]
	v_cvt_pk_bf16_f32 v194, v194, v195
	v_cvt_pk_bf16_f32 v195, v196, v197
	global_store_dwordx2 v230, v[194:195], s[56:57] sc1
	v_pk_mul_f32 v[198:199], v[198:199], v[220:221] op_sel_hi:[1,0]
	v_pk_mul_f32 v[200:201], v[200:201], v[220:221] op_sel_hi:[1,0]
	v_pk_fma_f32 v[198:199], v[198:199], v[68:69], v[84:85]
	v_pk_fma_f32 v[200:201], v[200:201], v[70:71], v[86:87]
	v_cvt_pk_bf16_f32 v198, v198, v199
	v_cvt_pk_bf16_f32 v199, v200, v201
	global_store_dwordx2 v230, v[198:199], s[56:57] offset:512 sc1
	v_pk_mul_f32 v[202:203], v[202:203], v[220:221] op_sel_hi:[1,0]
	v_pk_mul_f32 v[204:205], v[204:205], v[220:221] op_sel_hi:[1,0]
	v_pk_fma_f32 v[202:203], v[202:203], v[72:73], v[88:89]
	v_pk_fma_f32 v[204:205], v[204:205], v[74:75], v[90:91]
	v_cvt_pk_bf16_f32 v202, v202, v203
	v_cvt_pk_bf16_f32 v203, v204, v205
	global_store_dwordx2 v230, v[202:203], s[56:57] offset:1024 sc1
	v_pk_mul_f32 v[206:207], v[206:207], v[220:221] op_sel_hi:[1,0]
	v_pk_mul_f32 v[208:209], v[208:209], v[220:221] op_sel_hi:[1,0]
	v_pk_fma_f32 v[206:207], v[206:207], v[76:77], v[92:93]
	v_pk_fma_f32 v[208:209], v[208:209], v[78:79], v[94:95]
	v_cvt_pk_bf16_f32 v206, v206, v207
	v_cvt_pk_bf16_f32 v207, v208, v209
	global_store_dwordx2 v230, v[206:207], s[56:57] offset:1536 sc1
	s_add_u32 s56, s56, 0x400000
	s_addc_u32 s57, s57, 0

.Lxbn1_p1_ok:
	s_waitcnt vmcnt(0)
	s_add_u32 s28, s18, 0x3400
	s_addc_u32 s29, s19, 0
	global_atomic_add v0, v1, s[28:29]
	s_mul_i32 s21, s98, s100
	s_mov_b32 s22, 0

.LBB0_1259:
	s_or_b64 exec, exec, s[10:11]
	s_sext_i32_i8 s5, s26
	s_lshl_b32 s4, s4, 8
	s_lshl_b32 s10, s5, 6
	v_mov_b32_e32 v1, v170
	s_waitcnt lgkmcnt(0)
	s_barrier
	s_load_dwordx2 s[52:53], s[0:1], 0xe8
	s_add_i32 s66, s4, s10
	v_readfirstlane_b32 s65, v170
	v_and_b32_e32 v226, 63, v170
	v_mov_b32_e32 v228, 0x358637bd
	v_lshlrev_b32_e32 v227, 3, v226
	v_lshlrev_b32_e32 v226, 4, v226
	s_lshr_b32 s65, s65, 6
	s_add_i32 s66, s66, s65
	s_waitcnt lgkmcnt(0)
	s_sub_i32 s67, s66, 0x1000
	s_ashr_i32 s67, s67, 11
	s_add_i32 s67, s67, 1
	s_cmp_gt_i32 s66, 0xfff
	s_cselect_b32 s67, s67, 0
	s_add_i32 s67, s67, 0
	s_mul_i32 s67, s67, 6
	s_add_i32 s67, s67, 3
	s_lshl_b32 s67, s67, 12
	s_add_u32 s58, s52, 0x780000
	s_addc_u32 s59, s53, 0
	s_add_u32 s58, s58, s67
	s_addc_u32 s59, s59, 0
	s_add_u32 s60, s58, 0x1000
	s_addc_u32 s61, s59, 0
	global_load_dwordx4 v[178:181], v226, s[58:59]
	global_load_dwordx4 v[182:185], v226, s[58:59] offset:1024
	global_load_dwordx4 v[186:189], v226, s[58:59] offset:2048
	global_load_dwordx4 v[190:193], v226, s[58:59] offset:3072
	global_load_dwordx4 v[194:197], v226, s[60:61]
	global_load_dwordx4 v[198:201], v226, s[60:61] offset:1024
	global_load_dwordx4 v[202:205], v226, s[60:61] offset:2048
	global_load_dwordx4 v[206:209], v226, s[60:61] offset:3072
	s_lshl_b32 s67, s66, 11
	s_add_u32 s56, s52, 0x2ebc000
	s_addc_u32 s57, s53, 0
	s_add_u32 s56, s56, s67
	s_addc_u32 s57, s57, 0
	s_lshl_b32 s67, s66, 12
	s_add_u32 s54, s52, 0x46bc000
	s_addc_u32 s55, s53, 0
	s_add_u32 s54, s54, s67
	s_addc_u32 s55, s55, 0
	global_load_dwordx4 v[0:3], v226, s[54:55]
	global_load_dwordx4 v[4:7], v226, s[54:55] offset:1024
	global_load_dwordx4 v[8:11], v226, s[54:55] offset:2048
	global_load_dwordx4 v[12:15], v226, s[54:55] offset:3072
	s_add_u32 s54, s54, 0x8000
	s_addc_u32 s55, s55, 0
	global_load_dwordx4 v[16:19], v226, s[54:55]
	global_load_dwordx4 v[20:23], v226, s[54:55] offset:1024
	global_load_dwordx4 v[24:27], v226, s[54:55] offset:2048
	global_load_dwordx4 v[28:31], v226, s[54:55] offset:3072
	s_add_u32 s54, s54, 0x8000
	s_addc_u32 s55, s55, 0
	global_load_dwordx4 v[32:35], v226, s[54:55]
	global_load_dwordx4 v[36:39], v226, s[54:55] offset:1024
	global_load_dwordx4 v[40:43], v226, s[54:55] offset:2048
	global_load_dwordx4 v[44:47], v226, s[54:55] offset:3072
	s_add_u32 s54, s54, 0x8000
	s_addc_u32 s55, s55, 0
	global_load_dwordx4 v[48:51], v226, s[54:55]
	global_load_dwordx4 v[52:55], v226, s[54:55] offset:1024
	global_load_dwordx4 v[56:59], v226, s[54:55] offset:2048
	global_load_dwordx4 v[60:63], v226, s[54:55] offset:3072
	s_add_u32 s54, s54, 0x8000
	s_addc_u32 s55, s55, 0
	global_load_dwordx4 v[64:67], v226, s[54:55]
	global_load_dwordx4 v[68:71], v226, s[54:55] offset:1024
	global_load_dwordx4 v[72:75], v226, s[54:55] offset:2048
	global_load_dwordx4 v[76:79], v226, s[54:55] offset:3072
	s_add_u32 s54, s54, 0x8000
	s_addc_u32 s55, s55, 0
	global_load_dwordx4 v[80:83], v226, s[54:55]
	global_load_dwordx4 v[84:87], v226, s[54:55] offset:1024
	global_load_dwordx4 v[88:91], v226, s[54:55] offset:2048
	global_load_dwordx4 v[92:95], v226, s[54:55] offset:3072
	s_add_u32 s54, s54, 0x8000
	s_addc_u32 s55, s55, 0
	global_load_dwordx4 v[134:137], v226, s[54:55]
	global_load_dwordx4 v[138:141], v226, s[54:55] offset:1024
	global_load_dwordx4 v[142:145], v226, s[54:55] offset:2048
	global_load_dwordx4 v[146:149], v226, s[54:55] offset:3072
	s_add_u32 s54, s54, 0x8000
	s_addc_u32 s55, s55, 0
	global_load_dwordx4 v[150:153], v226, s[54:55]
	global_load_dwordx4 v[154:157], v226, s[54:55] offset:1024
	global_load_dwordx4 v[158:161], v226, s[54:55] offset:2048
	global_load_dwordx4 v[162:165], v226, s[54:55] offset:3072
	s_waitcnt vmcnt(28)
	v_mul_f32_e32 v210, v0, v0
	v_fmac_f32_e32 v210, v1, v1
	v_fmac_f32_e32 v210, v2, v2
	v_fmac_f32_e32 v210, v3, v3
	v_fmac_f32_e32 v210, v4, v4
	v_fmac_f32_e32 v210, v5, v5
	v_fmac_f32_e32 v210, v6, v6
	v_fmac_f32_e32 v210, v7, v7
	v_fmac_f32_e32 v210, v8, v8
	v_fmac_f32_e32 v210, v9, v9
	v_fmac_f32_e32 v210, v10, v10
	v_fmac_f32_e32 v210, v11, v11
	v_fmac_f32_e32 v210, v12, v12
	v_fmac_f32_e32 v210, v13, v13
	v_fmac_f32_e32 v210, v14, v14
	v_fmac_f32_e32 v210, v15, v15
	s_waitcnt vmcnt(24)
	v_mul_f32_e32 v212, v16, v16
	v_fmac_f32_e32 v212, v17, v17
	v_fmac_f32_e32 v212, v18, v18
	v_fmac_f32_e32 v212, v19, v19
	v_fmac_f32_e32 v212, v20, v20
	v_fmac_f32_e32 v212, v21, v21
	v_fmac_f32_e32 v212, v22, v22
	v_fmac_f32_e32 v212, v23, v23
	v_fmac_f32_e32 v212, v24, v24
	v_fmac_f32_e32 v212, v25, v25
	v_fmac_f32_e32 v212, v26, v26
	v_fmac_f32_e32 v212, v27, v27
	v_fmac_f32_e32 v212, v28, v28
	v_fmac_f32_e32 v212, v29, v29
	v_fmac_f32_e32 v212, v30, v30
	v_fmac_f32_e32 v212, v31, v31
	s_waitcnt vmcnt(20)
	v_mul_f32_e32 v214, v32, v32
	v_fmac_f32_e32 v214, v33, v33
	v_fmac_f32_e32 v214, v34, v34
	v_fmac_f32_e32 v214, v35, v35
	v_fmac_f32_e32 v214, v36, v36
	v_fmac_f32_e32 v214, v37, v37
	v_fmac_f32_e32 v214, v38, v38
	v_fmac_f32_e32 v214, v39, v39
	v_fmac_f32_e32 v214, v40, v40
	v_fmac_f32_e32 v214, v41, v41
	v_fmac_f32_e32 v214, v42, v42
	v_fmac_f32_e32 v214, v43, v43
	v_fmac_f32_e32 v214, v44, v44
	v_fmac_f32_e32 v214, v45, v45
	v_fmac_f32_e32 v214, v46, v46
	v_fmac_f32_e32 v214, v47, v47
	s_waitcnt vmcnt(16)
	v_mul_f32_e32 v216, v48, v48
	v_fmac_f32_e32 v216, v49, v49
	v_fmac_f32_e32 v216, v50, v50
	v_fmac_f32_e32 v216, v51, v51
	v_fmac_f32_e32 v216, v52, v52
	v_fmac_f32_e32 v216, v53, v53
	v_fmac_f32_e32 v216, v54, v54
	v_fmac_f32_e32 v216, v55, v55
	v_fmac_f32_e32 v216, v56, v56
	v_fmac_f32_e32 v216, v57, v57
	v_fmac_f32_e32 v216, v58, v58
	v_fmac_f32_e32 v216, v59, v59
	v_fmac_f32_e32 v216, v60, v60
	v_fmac_f32_e32 v216, v61, v61
	v_fmac_f32_e32 v216, v62, v62
	v_fmac_f32_e32 v216, v63, v63
	s_waitcnt vmcnt(12)
	v_mul_f32_e32 v218, v64, v64
	v_fmac_f32_e32 v218, v65, v65
	v_fmac_f32_e32 v218, v66, v66
	v_fmac_f32_e32 v218, v67, v67
	v_fmac_f32_e32 v218, v68, v68
	v_fmac_f32_e32 v218, v69, v69
	v_fmac_f32_e32 v218, v70, v70
	v_fmac_f32_e32 v218, v71, v71
	v_fmac_f32_e32 v218, v72, v72
	v_fmac_f32_e32 v218, v73, v73
	v_fmac_f32_e32 v218, v74, v74
	v_fmac_f32_e32 v218, v75, v75
	v_fmac_f32_e32 v218, v76, v76
	v_fmac_f32_e32 v218, v77, v77
	v_fmac_f32_e32 v218, v78, v78
	v_fmac_f32_e32 v218, v79, v79
	s_waitcnt vmcnt(8)
	v_mul_f32_e32 v220, v80, v80
	v_fmac_f32_e32 v220, v81, v81
	v_fmac_f32_e32 v220, v82, v82
	v_fmac_f32_e32 v220, v83, v83
	v_fmac_f32_e32 v220, v84, v84
	v_fmac_f32_e32 v220, v85, v85
	v_fmac_f32_e32 v220, v86, v86
	v_fmac_f32_e32 v220, v87, v87
	v_fmac_f32_e32 v220, v88, v88
	v_fmac_f32_e32 v220, v89, v89
	v_fmac_f32_e32 v220, v90, v90
	v_fmac_f32_e32 v220, v91, v91
	v_fmac_f32_e32 v220, v92, v92
	v_fmac_f32_e32 v220, v93, v93
	v_fmac_f32_e32 v220, v94, v94
	v_fmac_f32_e32 v220, v95, v95
	s_waitcnt vmcnt(4)
	v_mul_f32_e32 v222, v134, v134
	v_fmac_f32_e32 v222, v135, v135
	v_fmac_f32_e32 v222, v136, v136
	v_fmac_f32_e32 v222, v137, v137
	v_fmac_f32_e32 v222, v138, v138
	v_fmac_f32_e32 v222, v139, v139
	v_fmac_f32_e32 v222, v140, v140
	v_fmac_f32_e32 v222, v141, v141
	v_fmac_f32_e32 v222, v142, v142
	v_fmac_f32_e32 v222, v143, v143
	v_fmac_f32_e32 v222, v144, v144
	v_fmac_f32_e32 v222, v145, v145
	v_fmac_f32_e32 v222, v146, v146
	v_fmac_f32_e32 v222, v147, v147
	v_fmac_f32_e32 v222, v148, v148
	v_fmac_f32_e32 v222, v149, v149
	s_waitcnt vmcnt(0)
	v_mul_f32_e32 v224, v150, v150
	v_fmac_f32_e32 v224, v151, v151
	v_fmac_f32_e32 v224, v152, v152
	v_fmac_f32_e32 v224, v153, v153
	v_fmac_f32_e32 v224, v154, v154
	v_fmac_f32_e32 v224, v155, v155
	v_fmac_f32_e32 v224, v156, v156
	v_fmac_f32_e32 v224, v157, v157
	v_fmac_f32_e32 v224, v158, v158
	v_fmac_f32_e32 v224, v159, v159
	v_fmac_f32_e32 v224, v160, v160
	v_fmac_f32_e32 v224, v161, v161
	v_fmac_f32_e32 v224, v162, v162
	v_fmac_f32_e32 v224, v163, v163
	v_fmac_f32_e32 v224, v164, v164
	v_fmac_f32_e32 v224, v165, v165
	ds_bpermute_b32 v211, v171, v210
	ds_bpermute_b32 v213, v171, v212
	ds_bpermute_b32 v215, v171, v214
	ds_bpermute_b32 v217, v171, v216
	ds_bpermute_b32 v219, v171, v218
	ds_bpermute_b32 v221, v171, v220
	ds_bpermute_b32 v223, v171, v222
	ds_bpermute_b32 v225, v171, v224
	s_waitcnt lgkmcnt(7)
	v_add_f32_e32 v210, v210, v211
	s_waitcnt lgkmcnt(6)
	v_add_f32_e32 v212, v212, v213
	s_waitcnt lgkmcnt(5)
	v_add_f32_e32 v214, v214, v215
	s_waitcnt lgkmcnt(4)
	v_add_f32_e32 v216, v216, v217
	s_waitcnt lgkmcnt(3)
	v_add_f32_e32 v218, v218, v219
	s_waitcnt lgkmcnt(2)
	v_add_f32_e32 v220, v220, v221
	s_waitcnt lgkmcnt(1)
	v_add_f32_e32 v222, v222, v223
	s_waitcnt lgkmcnt(0)
	v_add_f32_e32 v224, v224, v225
	ds_bpermute_b32 v211, v172, v210
	ds_bpermute_b32 v213, v172, v212
	ds_bpermute_b32 v215, v172, v214
	ds_bpermute_b32 v217, v172, v216
	ds_bpermute_b32 v219, v172, v218
	ds_bpermute_b32 v221, v172, v220
	ds_bpermute_b32 v223, v172, v222
	ds_bpermute_b32 v225, v172, v224
	s_waitcnt lgkmcnt(7)
	v_add_f32_e32 v210, v210, v211
	s_waitcnt lgkmcnt(6)
	v_add_f32_e32 v212, v212, v213
	s_waitcnt lgkmcnt(5)
	v_add_f32_e32 v214, v214, v215
	s_waitcnt lgkmcnt(4)
	v_add_f32_e32 v216, v216, v217
	s_waitcnt lgkmcnt(3)
	v_add_f32_e32 v218, v218, v219
	s_waitcnt lgkmcnt(2)
	v_add_f32_e32 v220, v220, v221
	s_waitcnt lgkmcnt(1)
	v_add_f32_e32 v222, v222, v223
	s_waitcnt lgkmcnt(0)
	v_add_f32_e32 v224, v224, v225
	ds_bpermute_b32 v211, v173, v210
	ds_bpermute_b32 v213, v173, v212
	ds_bpermute_b32 v215, v173, v214
	ds_bpermute_b32 v217, v173, v216
	ds_bpermute_b32 v219, v173, v218
	ds_bpermute_b32 v221, v173, v220
	ds_bpermute_b32 v223, v173, v222
	ds_bpermute_b32 v225, v173, v224
	s_waitcnt lgkmcnt(7)
	v_add_f32_e32 v210, v210, v211
	s_waitcnt lgkmcnt(6)
	v_add_f32_e32 v212, v212, v213
	s_waitcnt lgkmcnt(5)
	v_add_f32_e32 v214, v214, v215
	s_waitcnt lgkmcnt(4)
	v_add_f32_e32 v216, v216, v217
	s_waitcnt lgkmcnt(3)
	v_add_f32_e32 v218, v218, v219
	s_waitcnt lgkmcnt(2)
	v_add_f32_e32 v220, v220, v221
	s_waitcnt lgkmcnt(1)
	v_add_f32_e32 v222, v222, v223
	s_waitcnt lgkmcnt(0)
	v_add_f32_e32 v224, v224, v225
	ds_bpermute_b32 v211, v174, v210
	ds_bpermute_b32 v213, v174, v212
	ds_bpermute_b32 v215, v174, v214
	ds_bpermute_b32 v217, v174, v216
	ds_bpermute_b32 v219, v174, v218
	ds_bpermute_b32 v221, v174, v220
	ds_bpermute_b32 v223, v174, v222
	ds_bpermute_b32 v225, v174, v224
	s_waitcnt lgkmcnt(7)
	v_add_f32_e32 v210, v210, v211
	s_waitcnt lgkmcnt(6)
	v_add_f32_e32 v212, v212, v213
	s_waitcnt lgkmcnt(5)
	v_add_f32_e32 v214, v214, v215
	s_waitcnt lgkmcnt(4)
	v_add_f32_e32 v216, v216, v217
	s_waitcnt lgkmcnt(3)
	v_add_f32_e32 v218, v218, v219
	s_waitcnt lgkmcnt(2)
	v_add_f32_e32 v220, v220, v221
	s_waitcnt lgkmcnt(1)
	v_add_f32_e32 v222, v222, v223
	s_waitcnt lgkmcnt(0)
	v_add_f32_e32 v224, v224, v225
	ds_bpermute_b32 v211, v175, v210
	ds_bpermute_b32 v213, v175, v212
	ds_bpermute_b32 v215, v175, v214
	ds_bpermute_b32 v217, v175, v216
	ds_bpermute_b32 v219, v175, v218
	ds_bpermute_b32 v221, v175, v220
	ds_bpermute_b32 v223, v175, v222
	ds_bpermute_b32 v225, v175, v224
	s_waitcnt lgkmcnt(7)
	v_add_f32_e32 v210, v210, v211
	s_waitcnt lgkmcnt(6)
	v_add_f32_e32 v212, v212, v213
	s_waitcnt lgkmcnt(5)
	v_add_f32_e32 v214, v214, v215
	s_waitcnt lgkmcnt(4)
	v_add_f32_e32 v216, v216, v217
	s_waitcnt lgkmcnt(3)
	v_add_f32_e32 v218, v218, v219
	s_waitcnt lgkmcnt(2)
	v_add_f32_e32 v220, v220, v221
	s_waitcnt lgkmcnt(1)
	v_add_f32_e32 v222, v222, v223
	s_waitcnt lgkmcnt(0)
	v_add_f32_e32 v224, v224, v225
	ds_bpermute_b32 v211, v176, v210
	ds_bpermute_b32 v213, v176, v212
	ds_bpermute_b32 v215, v176, v214
	ds_bpermute_b32 v217, v176, v216
	ds_bpermute_b32 v219, v176, v218
	ds_bpermute_b32 v221, v176, v220
	ds_bpermute_b32 v223, v176, v222
	ds_bpermute_b32 v225, v176, v224
	s_waitcnt lgkmcnt(7)
	v_add_f32_e32 v210, v210, v211
	s_waitcnt lgkmcnt(6)
	v_add_f32_e32 v212, v212, v213
	s_waitcnt lgkmcnt(5)
	v_add_f32_e32 v214, v214, v215
	s_waitcnt lgkmcnt(4)
	v_add_f32_e32 v216, v216, v217
	s_waitcnt lgkmcnt(3)
	v_add_f32_e32 v218, v218, v219
	s_waitcnt lgkmcnt(2)
	v_add_f32_e32 v220, v220, v221
	s_waitcnt lgkmcnt(1)
	v_add_f32_e32 v222, v222, v223
	s_waitcnt lgkmcnt(0)
	v_add_f32_e32 v224, v224, v225
	v_fmamk_f32 v210, v210, 0x3a800000, v228
	v_fmamk_f32 v212, v212, 0x3a800000, v228
	v_fmamk_f32 v214, v214, 0x3a800000, v228
	v_fmamk_f32 v216, v216, 0x3a800000, v228
	v_fmamk_f32 v218, v218, 0x3a800000, v228
	v_fmamk_f32 v220, v220, 0x3a800000, v228
	v_fmamk_f32 v222, v222, 0x3a800000, v228
	v_fmamk_f32 v224, v224, 0x3a800000, v228
	v_rsq_f32_e32 v210, v210
	v_rsq_f32_e32 v212, v212
	v_rsq_f32_e32 v214, v214
	v_rsq_f32_e32 v216, v216
	v_rsq_f32_e32 v218, v218
	v_rsq_f32_e32 v220, v220
	v_rsq_f32_e32 v222, v222
	v_rsq_f32_e32 v224, v224
	v_pk_mul_f32 v[0:1], v[0:1], v[210:211] op_sel_hi:[1,0]
	v_pk_mul_f32 v[2:3], v[2:3], v[210:211] op_sel_hi:[1,0]
	v_pk_fma_f32 v[0:1], v[0:1], v[178:179], v[194:195]
	v_pk_fma_f32 v[2:3], v[2:3], v[180:181], v[196:197]
	v_cvt_pk_bf16_f32 v0, v0, v1
	v_cvt_pk_bf16_f32 v1, v2, v3
	global_store_dwordx2 v227, v[0:1], s[56:57] sc1
	v_pk_mul_f32 v[4:5], v[4:5], v[210:211] op_sel_hi:[1,0]
	v_pk_mul_f32 v[6:7], v[6:7], v[210:211] op_sel_hi:[1,0]
	v_pk_fma_f32 v[4:5], v[4:5], v[182:183], v[198:199]
	v_pk_fma_f32 v[6:7], v[6:7], v[184:185], v[200:201]
	v_cvt_pk_bf16_f32 v4, v4, v5
	v_cvt_pk_bf16_f32 v5, v6, v7
	global_store_dwordx2 v227, v[4:5], s[56:57] offset:512 sc1
	v_pk_mul_f32 v[8:9], v[8:9], v[210:211] op_sel_hi:[1,0]
	v_pk_mul_f32 v[10:11], v[10:11], v[210:211] op_sel_hi:[1,0]
	v_pk_fma_f32 v[8:9], v[8:9], v[186:187], v[202:203]
	v_pk_fma_f32 v[10:11], v[10:11], v[188:189], v[204:205]
	v_cvt_pk_bf16_f32 v8, v8, v9
	v_cvt_pk_bf16_f32 v9, v10, v11
	global_store_dwordx2 v227, v[8:9], s[56:57] offset:1024 sc1
	v_pk_mul_f32 v[12:13], v[12:13], v[210:211] op_sel_hi:[1,0]
	v_pk_mul_f32 v[14:15], v[14:15], v[210:211] op_sel_hi:[1,0]
	v_pk_fma_f32 v[12:13], v[12:13], v[190:191], v[206:207]
	v_pk_fma_f32 v[14:15], v[14:15], v[192:193], v[208:209]
	v_cvt_pk_bf16_f32 v12, v12, v13
	v_cvt_pk_bf16_f32 v13, v14, v15
	global_store_dwordx2 v227, v[12:13], s[56:57] offset:1536 sc1
	s_add_u32 s56, s56, 0x4000
	s_addc_u32 s57, s57, 0
	v_pk_mul_f32 v[16:17], v[16:17], v[212:213] op_sel_hi:[1,0]
	v_pk_mul_f32 v[18:19], v[18:19], v[212:213] op_sel_hi:[1,0]
	v_pk_fma_f32 v[16:17], v[16:17], v[178:179], v[194:195]
	v_pk_fma_f32 v[18:19], v[18:19], v[180:181], v[196:197]
	v_cvt_pk_bf16_f32 v16, v16, v17
	v_cvt_pk_bf16_f32 v17, v18, v19
	global_store_dwordx2 v227, v[16:17], s[56:57] sc1
	v_pk_mul_f32 v[20:21], v[20:21], v[212:213] op_sel_hi:[1,0]
	v_pk_mul_f32 v[22:23], v[22:23], v[212:213] op_sel_hi:[1,0]
	v_pk_fma_f32 v[20:21], v[20:21], v[182:183], v[198:199]
	v_pk_fma_f32 v[22:23], v[22:23], v[184:185], v[200:201]
	v_cvt_pk_bf16_f32 v20, v20, v21
	v_cvt_pk_bf16_f32 v21, v22, v23
	global_store_dwordx2 v227, v[20:21], s[56:57] offset:512 sc1
	v_pk_mul_f32 v[24:25], v[24:25], v[212:213] op_sel_hi:[1,0]
	v_pk_mul_f32 v[26:27], v[26:27], v[212:213] op_sel_hi:[1,0]
	v_pk_fma_f32 v[24:25], v[24:25], v[186:187], v[202:203]
	v_pk_fma_f32 v[26:27], v[26:27], v[188:189], v[204:205]
	v_cvt_pk_bf16_f32 v24, v24, v25
	v_cvt_pk_bf16_f32 v25, v26, v27
	global_store_dwordx2 v227, v[24:25], s[56:57] offset:1024 sc1
	v_pk_mul_f32 v[28:29], v[28:29], v[212:213] op_sel_hi:[1,0]
	v_pk_mul_f32 v[30:31], v[30:31], v[212:213] op_sel_hi:[1,0]
	v_pk_fma_f32 v[28:29], v[28:29], v[190:191], v[206:207]
	v_pk_fma_f32 v[30:31], v[30:31], v[192:193], v[208:209]
	v_cvt_pk_bf16_f32 v28, v28, v29
	v_cvt_pk_bf16_f32 v29, v30, v31
	global_store_dwordx2 v227, v[28:29], s[56:57] offset:1536 sc1
	s_add_u32 s56, s56, 0x4000
	s_addc_u32 s57, s57, 0
	v_pk_mul_f32 v[32:33], v[32:33], v[214:215] op_sel_hi:[1,0]
	v_pk_mul_f32 v[34:35], v[34:35], v[214:215] op_sel_hi:[1,0]
	v_pk_fma_f32 v[32:33], v[32:33], v[178:179], v[194:195]
	v_pk_fma_f32 v[34:35], v[34:35], v[180:181], v[196:197]
	v_cvt_pk_bf16_f32 v32, v32, v33
	v_cvt_pk_bf16_f32 v33, v34, v35
	global_store_dwordx2 v227, v[32:33], s[56:57] sc1
	v_pk_mul_f32 v[36:37], v[36:37], v[214:215] op_sel_hi:[1,0]
	v_pk_mul_f32 v[38:39], v[38:39], v[214:215] op_sel_hi:[1,0]
	v_pk_fma_f32 v[36:37], v[36:37], v[182:183], v[198:199]
	v_pk_fma_f32 v[38:39], v[38:39], v[184:185], v[200:201]
	v_cvt_pk_bf16_f32 v36, v36, v37
	v_cvt_pk_bf16_f32 v37, v38, v39
	global_store_dwordx2 v227, v[36:37], s[56:57] offset:512 sc1
	v_pk_mul_f32 v[40:41], v[40:41], v[214:215] op_sel_hi:[1,0]
	v_pk_mul_f32 v[42:43], v[42:43], v[214:215] op_sel_hi:[1,0]
	v_pk_fma_f32 v[40:41], v[40:41], v[186:187], v[202:203]
	v_pk_fma_f32 v[42:43], v[42:43], v[188:189], v[204:205]
	v_cvt_pk_bf16_f32 v40, v40, v41
	v_cvt_pk_bf16_f32 v41, v42, v43
	global_store_dwordx2 v227, v[40:41], s[56:57] offset:1024 sc1
	v_pk_mul_f32 v[44:45], v[44:45], v[214:215] op_sel_hi:[1,0]
	v_pk_mul_f32 v[46:47], v[46:47], v[214:215] op_sel_hi:[1,0]
	v_pk_fma_f32 v[44:45], v[44:45], v[190:191], v[206:207]
	v_pk_fma_f32 v[46:47], v[46:47], v[192:193], v[208:209]
	v_cvt_pk_bf16_f32 v44, v44, v45
	v_cvt_pk_bf16_f32 v45, v46, v47
	global_store_dwordx2 v227, v[44:45], s[56:57] offset:1536 sc1
	s_add_u32 s56, s56, 0x4000
	s_addc_u32 s57, s57, 0
	v_pk_mul_f32 v[48:49], v[48:49], v[216:217] op_sel_hi:[1,0]
	v_pk_mul_f32 v[50:51], v[50:51], v[216:217] op_sel_hi:[1,0]
	v_pk_fma_f32 v[48:49], v[48:49], v[178:179], v[194:195]
	v_pk_fma_f32 v[50:51], v[50:51], v[180:181], v[196:197]
	v_cvt_pk_bf16_f32 v48, v48, v49
	v_cvt_pk_bf16_f32 v49, v50, v51
	global_store_dwordx2 v227, v[48:49], s[56:57] sc1
	v_pk_mul_f32 v[52:53], v[52:53], v[216:217] op_sel_hi:[1,0]
	v_pk_mul_f32 v[54:55], v[54:55], v[216:217] op_sel_hi:[1,0]
	v_pk_fma_f32 v[52:53], v[52:53], v[182:183], v[198:199]
	v_pk_fma_f32 v[54:55], v[54:55], v[184:185], v[200:201]
	v_cvt_pk_bf16_f32 v52, v52, v53
	v_cvt_pk_bf16_f32 v53, v54, v55
	global_store_dwordx2 v227, v[52:53], s[56:57] offset:512 sc1
	v_pk_mul_f32 v[56:57], v[56:57], v[216:217] op_sel_hi:[1,0]
	v_pk_mul_f32 v[58:59], v[58:59], v[216:217] op_sel_hi:[1,0]
	v_pk_fma_f32 v[56:57], v[56:57], v[186:187], v[202:203]
	v_pk_fma_f32 v[58:59], v[58:59], v[188:189], v[204:205]
	v_cvt_pk_bf16_f32 v56, v56, v57
	v_cvt_pk_bf16_f32 v57, v58, v59
	global_store_dwordx2 v227, v[56:57], s[56:57] offset:1024 sc1
	v_pk_mul_f32 v[60:61], v[60:61], v[216:217] op_sel_hi:[1,0]
	v_pk_mul_f32 v[62:63], v[62:63], v[216:217] op_sel_hi:[1,0]
	v_pk_fma_f32 v[60:61], v[60:61], v[190:191], v[206:207]
	v_pk_fma_f32 v[62:63], v[62:63], v[192:193], v[208:209]
	v_cvt_pk_bf16_f32 v60, v60, v61
	v_cvt_pk_bf16_f32 v61, v62, v63
	global_store_dwordx2 v227, v[60:61], s[56:57] offset:1536 sc1
	s_add_u32 s56, s56, 0x4000
	s_addc_u32 s57, s57, 0
	v_pk_mul_f32 v[64:65], v[64:65], v[218:219] op_sel_hi:[1,0]
	v_pk_mul_f32 v[66:67], v[66:67], v[218:219] op_sel_hi:[1,0]
	v_pk_fma_f32 v[64:65], v[64:65], v[178:179], v[194:195]
	v_pk_fma_f32 v[66:67], v[66:67], v[180:181], v[196:197]
	v_cvt_pk_bf16_f32 v64, v64, v65
	v_cvt_pk_bf16_f32 v65, v66, v67
	global_store_dwordx2 v227, v[64:65], s[56:57] sc1
	v_pk_mul_f32 v[68:69], v[68:69], v[218:219] op_sel_hi:[1,0]
	v_pk_mul_f32 v[70:71], v[70:71], v[218:219] op_sel_hi:[1,0]
	v_pk_fma_f32 v[68:69], v[68:69], v[182:183], v[198:199]
	v_pk_fma_f32 v[70:71], v[70:71], v[184:185], v[200:201]
	v_cvt_pk_bf16_f32 v68, v68, v69
	v_cvt_pk_bf16_f32 v69, v70, v71
	global_store_dwordx2 v227, v[68:69], s[56:57] offset:512 sc1
	v_pk_mul_f32 v[72:73], v[72:73], v[218:219] op_sel_hi:[1,0]
	v_pk_mul_f32 v[74:75], v[74:75], v[218:219] op_sel_hi:[1,0]
	v_pk_fma_f32 v[72:73], v[72:73], v[186:187], v[202:203]
	v_pk_fma_f32 v[74:75], v[74:75], v[188:189], v[204:205]
	v_cvt_pk_bf16_f32 v72, v72, v73
	v_cvt_pk_bf16_f32 v73, v74, v75
	global_store_dwordx2 v227, v[72:73], s[56:57] offset:1024 sc1
	v_pk_mul_f32 v[76:77], v[76:77], v[218:219] op_sel_hi:[1,0]
	v_pk_mul_f32 v[78:79], v[78:79], v[218:219] op_sel_hi:[1,0]
	v_pk_fma_f32 v[76:77], v[76:77], v[190:191], v[206:207]
	v_pk_fma_f32 v[78:79], v[78:79], v[192:193], v[208:209]
	v_cvt_pk_bf16_f32 v76, v76, v77
	v_cvt_pk_bf16_f32 v77, v78, v79
	global_store_dwordx2 v227, v[76:77], s[56:57] offset:1536 sc1
	s_add_u32 s56, s56, 0x4000
	s_addc_u32 s57, s57, 0
	v_pk_mul_f32 v[80:81], v[80:81], v[220:221] op_sel_hi:[1,0]
	v_pk_mul_f32 v[82:83], v[82:83], v[220:221] op_sel_hi:[1,0]
	v_pk_fma_f32 v[80:81], v[80:81], v[178:179], v[194:195]
	v_pk_fma_f32 v[82:83], v[82:83], v[180:181], v[196:197]
	v_cvt_pk_bf16_f32 v80, v80, v81
	v_cvt_pk_bf16_f32 v81, v82, v83
	global_store_dwordx2 v227, v[80:81], s[56:57] sc1
	v_pk_mul_f32 v[84:85], v[84:85], v[220:221] op_sel_hi:[1,0]
	v_pk_mul_f32 v[86:87], v[86:87], v[220:221] op_sel_hi:[1,0]
	v_pk_fma_f32 v[84:85], v[84:85], v[182:183], v[198:199]
	v_pk_fma_f32 v[86:87], v[86:87], v[184:185], v[200:201]
	v_cvt_pk_bf16_f32 v84, v84, v85
	v_cvt_pk_bf16_f32 v85, v86, v87
	global_store_dwordx2 v227, v[84:85], s[56:57] offset:512 sc1
	v_pk_mul_f32 v[88:89], v[88:89], v[220:221] op_sel_hi:[1,0]
	v_pk_mul_f32 v[90:91], v[90:91], v[220:221] op_sel_hi:[1,0]
	v_pk_fma_f32 v[88:89], v[88:89], v[186:187], v[202:203]
	v_pk_fma_f32 v[90:91], v[90:91], v[188:189], v[204:205]
	v_cvt_pk_bf16_f32 v88, v88, v89
	v_cvt_pk_bf16_f32 v89, v90, v91
	global_store_dwordx2 v227, v[88:89], s[56:57] offset:1024 sc1
	v_pk_mul_f32 v[92:93], v[92:93], v[220:221] op_sel_hi:[1,0]
	v_pk_mul_f32 v[94:95], v[94:95], v[220:221] op_sel_hi:[1,0]
	v_pk_fma_f32 v[92:93], v[92:93], v[190:191], v[206:207]
	v_pk_fma_f32 v[94:95], v[94:95], v[192:193], v[208:209]
	v_cvt_pk_bf16_f32 v92, v92, v93
	v_cvt_pk_bf16_f32 v93, v94, v95
	global_store_dwordx2 v227, v[92:93], s[56:57] offset:1536 sc1
	s_add_u32 s56, s56, 0x4000
	s_addc_u32 s57, s57, 0
	v_pk_mul_f32 v[134:135], v[134:135], v[222:223] op_sel_hi:[1,0]
	v_pk_mul_f32 v[136:137], v[136:137], v[222:223] op_sel_hi:[1,0]
	v_pk_fma_f32 v[134:135], v[134:135], v[178:179], v[194:195]
	v_pk_fma_f32 v[136:137], v[136:137], v[180:181], v[196:197]
	v_cvt_pk_bf16_f32 v134, v134, v135
	v_cvt_pk_bf16_f32 v135, v136, v137
	global_store_dwordx2 v227, v[134:135], s[56:57] sc1
	v_pk_mul_f32 v[138:139], v[138:139], v[222:223] op_sel_hi:[1,0]
	v_pk_mul_f32 v[140:141], v[140:141], v[222:223] op_sel_hi:[1,0]
	v_pk_fma_f32 v[138:139], v[138:139], v[182:183], v[198:199]
	v_pk_fma_f32 v[140:141], v[140:141], v[184:185], v[200:201]
	v_cvt_pk_bf16_f32 v138, v138, v139
	v_cvt_pk_bf16_f32 v139, v140, v141
	global_store_dwordx2 v227, v[138:139], s[56:57] offset:512 sc1
	v_pk_mul_f32 v[142:143], v[142:143], v[222:223] op_sel_hi:[1,0]
	v_pk_mul_f32 v[144:145], v[144:145], v[222:223] op_sel_hi:[1,0]
	v_pk_fma_f32 v[142:143], v[142:143], v[186:187], v[202:203]
	v_pk_fma_f32 v[144:145], v[144:145], v[188:189], v[204:205]
	v_cvt_pk_bf16_f32 v142, v142, v143
	v_cvt_pk_bf16_f32 v143, v144, v145
	global_store_dwordx2 v227, v[142:143], s[56:57] offset:1024 sc1
	v_pk_mul_f32 v[146:147], v[146:147], v[222:223] op_sel_hi:[1,0]
	v_pk_mul_f32 v[148:149], v[148:149], v[222:223] op_sel_hi:[1,0]
	v_pk_fma_f32 v[146:147], v[146:147], v[190:191], v[206:207]
	v_pk_fma_f32 v[148:149], v[148:149], v[192:193], v[208:209]
	v_cvt_pk_bf16_f32 v146, v146, v147
	v_cvt_pk_bf16_f32 v147, v148, v149
	global_store_dwordx2 v227, v[146:147], s[56:57] offset:1536 sc1
	s_add_u32 s56, s56, 0x4000
	s_addc_u32 s57, s57, 0
	v_pk_mul_f32 v[150:151], v[150:151], v[224:225] op_sel_hi:[1,0]
	v_pk_mul_f32 v[152:153], v[152:153], v[224:225] op_sel_hi:[1,0]
	v_pk_fma_f32 v[150:151], v[150:151], v[178:179], v[194:195]
	v_pk_fma_f32 v[152:153], v[152:153], v[180:181], v[196:197]
	v_cvt_pk_bf16_f32 v150, v150, v151
	v_cvt_pk_bf16_f32 v151, v152, v153
	global_store_dwordx2 v227, v[150:151], s[56:57] sc1
	v_pk_mul_f32 v[154:155], v[154:155], v[224:225] op_sel_hi:[1,0]
	v_pk_mul_f32 v[156:157], v[156:157], v[224:225] op_sel_hi:[1,0]
	v_pk_fma_f32 v[154:155], v[154:155], v[182:183], v[198:199]
	v_pk_fma_f32 v[156:157], v[156:157], v[184:185], v[200:201]
	v_cvt_pk_bf16_f32 v154, v154, v155
	v_cvt_pk_bf16_f32 v155, v156, v157
	global_store_dwordx2 v227, v[154:155], s[56:57] offset:512 sc1
	v_pk_mul_f32 v[158:159], v[158:159], v[224:225] op_sel_hi:[1,0]
	v_pk_mul_f32 v[160:161], v[160:161], v[224:225] op_sel_hi:[1,0]
	v_pk_fma_f32 v[158:159], v[158:159], v[186:187], v[202:203]
	v_pk_fma_f32 v[160:161], v[160:161], v[188:189], v[204:205]
	v_cvt_pk_bf16_f32 v158, v158, v159
	v_cvt_pk_bf16_f32 v159, v160, v161
	global_store_dwordx2 v227, v[158:159], s[56:57] offset:1024 sc1
	v_pk_mul_f32 v[162:163], v[162:163], v[224:225] op_sel_hi:[1,0]
	v_pk_mul_f32 v[164:165], v[164:165], v[224:225] op_sel_hi:[1,0]
	v_pk_fma_f32 v[162:163], v[162:163], v[190:191], v[206:207]
	v_pk_fma_f32 v[164:165], v[164:165], v[192:193], v[208:209]
	v_cvt_pk_bf16_f32 v162, v162, v163
	v_cvt_pk_bf16_f32 v163, v164, v165
	global_store_dwordx2 v227, v[162:163], s[56:57] offset:1536 sc1

.LBB0_1848:
	s_or_b64 exec, exec, s[20:21]
	s_sext_i32_i8 s13, s30
	s_lshl_b32 s12, s12, 8
	s_lshl_b32 s13, s13, 6
	s_add_i32 s36, s12, s13
	v_mov_b32_e32 v1, v170
	s_barrier
	s_load_dwordx2 s[52:53], s[0:1], 0xe8
	s_mov_b32 s66, s36
	v_readfirstlane_b32 s65, v170
	v_and_b32_e32 v226, 63, v170
	v_mov_b32_e32 v228, 0x358637bd
	v_lshlrev_b32_e32 v227, 3, v226
	v_lshlrev_b32_e32 v226, 4, v226
	s_lshr_b32 s65, s65, 6
	s_add_i32 s66, s66, s65
	s_waitcnt lgkmcnt(0)
	s_sub_i32 s67, s66, 0x1000
	s_ashr_i32 s67, s67, 11
	s_add_i32 s67, s67, 1
	s_cmp_gt_i32 s66, 0xfff
	s_cselect_b32 s67, s67, 0
	s_add_i32 s67, s67, 5
	s_mul_i32 s67, s67, 6
	s_add_i32 s67, s67, 3
	s_lshl_b32 s67, s67, 12
	s_add_u32 s58, s52, 0x780000
	s_addc_u32 s59, s53, 0
	s_add_u32 s58, s58, s67
	s_addc_u32 s59, s59, 0
	s_add_u32 s60, s58, 0x1000
	s_addc_u32 s61, s59, 0
	global_load_dwordx4 v[178:181], v226, s[58:59]
	global_load_dwordx4 v[182:185], v226, s[58:59] offset:1024
	global_load_dwordx4 v[186:189], v226, s[58:59] offset:2048
	global_load_dwordx4 v[190:193], v226, s[58:59] offset:3072
	global_load_dwordx4 v[194:197], v226, s[60:61]
	global_load_dwordx4 v[198:201], v226, s[60:61] offset:1024
	global_load_dwordx4 v[202:205], v226, s[60:61] offset:2048
	global_load_dwordx4 v[206:209], v226, s[60:61] offset:3072
	s_lshl_b32 s67, s66, 11
	s_add_u32 s56, s52, 0x2ebc000
	s_addc_u32 s57, s53, 0
	s_add_u32 s56, s56, s67
	s_addc_u32 s57, s57, 0
	s_lshl_b32 s67, s66, 12
	s_add_u32 s54, s52, 0x46bc000
	s_addc_u32 s55, s53, 0
	s_add_u32 s54, s54, s67
	s_addc_u32 s55, s55, 0
	global_load_dwordx4 v[0:3], v226, s[54:55]
	global_load_dwordx4 v[4:7], v226, s[54:55] offset:1024
	global_load_dwordx4 v[8:11], v226, s[54:55] offset:2048
	global_load_dwordx4 v[12:15], v226, s[54:55] offset:3072
	s_add_u32 s54, s54, 0x8000
	s_addc_u32 s55, s55, 0
	global_load_dwordx4 v[16:19], v226, s[54:55]
	global_load_dwordx4 v[20:23], v226, s[54:55] offset:1024
	global_load_dwordx4 v[24:27], v226, s[54:55] offset:2048
	global_load_dwordx4 v[28:31], v226, s[54:55] offset:3072
	s_add_u32 s54, s54, 0x8000
	s_addc_u32 s55, s55, 0
	global_load_dwordx4 v[32:35], v226, s[54:55]
	global_load_dwordx4 v[36:39], v226, s[54:55] offset:1024
	global_load_dwordx4 v[40:43], v226, s[54:55] offset:2048
	global_load_dwordx4 v[44:47], v226, s[54:55] offset:3072
	s_add_u32 s54, s54, 0x8000
	s_addc_u32 s55, s55, 0
	global_load_dwordx4 v[48:51], v226, s[54:55]
	global_load_dwordx4 v[52:55], v226, s[54:55] offset:1024
	global_load_dwordx4 v[56:59], v226, s[54:55] offset:2048
	global_load_dwordx4 v[60:63], v226, s[54:55] offset:3072
	s_add_u32 s54, s54, 0x8000
	s_addc_u32 s55, s55, 0
	global_load_dwordx4 v[64:67], v226, s[54:55]
	global_load_dwordx4 v[68:71], v226, s[54:55] offset:1024
	global_load_dwordx4 v[72:75], v226, s[54:55] offset:2048
	global_load_dwordx4 v[76:79], v226, s[54:55] offset:3072
	s_add_u32 s54, s54, 0x8000
	s_addc_u32 s55, s55, 0
	global_load_dwordx4 v[80:83], v226, s[54:55]
	global_load_dwordx4 v[84:87], v226, s[54:55] offset:1024
	global_load_dwordx4 v[88:91], v226, s[54:55] offset:2048
	global_load_dwordx4 v[92:95], v226, s[54:55] offset:3072
	s_add_u32 s54, s54, 0x8000
	s_addc_u32 s55, s55, 0
	global_load_dwordx4 v[134:137], v226, s[54:55]
	global_load_dwordx4 v[138:141], v226, s[54:55] offset:1024
	global_load_dwordx4 v[142:145], v226, s[54:55] offset:2048
	global_load_dwordx4 v[146:149], v226, s[54:55] offset:3072
	s_add_u32 s54, s54, 0x8000
	s_addc_u32 s55, s55, 0
	global_load_dwordx4 v[150:153], v226, s[54:55]
	global_load_dwordx4 v[154:157], v226, s[54:55] offset:1024
	global_load_dwordx4 v[158:161], v226, s[54:55] offset:2048
	global_load_dwordx4 v[162:165], v226, s[54:55] offset:3072
	s_waitcnt vmcnt(28)
	v_mul_f32_e32 v210, v0, v0
	v_fmac_f32_e32 v210, v1, v1
	v_fmac_f32_e32 v210, v2, v2
	v_fmac_f32_e32 v210, v3, v3
	v_fmac_f32_e32 v210, v4, v4
	v_fmac_f32_e32 v210, v5, v5
	v_fmac_f32_e32 v210, v6, v6
	v_fmac_f32_e32 v210, v7, v7
	v_fmac_f32_e32 v210, v8, v8
	v_fmac_f32_e32 v210, v9, v9
	v_fmac_f32_e32 v210, v10, v10
	v_fmac_f32_e32 v210, v11, v11
	v_fmac_f32_e32 v210, v12, v12
	v_fmac_f32_e32 v210, v13, v13
	v_fmac_f32_e32 v210, v14, v14
	v_fmac_f32_e32 v210, v15, v15
	s_waitcnt vmcnt(24)
	v_mul_f32_e32 v212, v16, v16
	v_fmac_f32_e32 v212, v17, v17
	v_fmac_f32_e32 v212, v18, v18
	v_fmac_f32_e32 v212, v19, v19
	v_fmac_f32_e32 v212, v20, v20
	v_fmac_f32_e32 v212, v21, v21
	v_fmac_f32_e32 v212, v22, v22
	v_fmac_f32_e32 v212, v23, v23
	v_fmac_f32_e32 v212, v24, v24
	v_fmac_f32_e32 v212, v25, v25
	v_fmac_f32_e32 v212, v26, v26
	v_fmac_f32_e32 v212, v27, v27
	v_fmac_f32_e32 v212, v28, v28
	v_fmac_f32_e32 v212, v29, v29
	v_fmac_f32_e32 v212, v30, v30
	v_fmac_f32_e32 v212, v31, v31
	s_waitcnt vmcnt(20)
	v_mul_f32_e32 v214, v32, v32
	v_fmac_f32_e32 v214, v33, v33
	v_fmac_f32_e32 v214, v34, v34
	v_fmac_f32_e32 v214, v35, v35
	v_fmac_f32_e32 v214, v36, v36
	v_fmac_f32_e32 v214, v37, v37
	v_fmac_f32_e32 v214, v38, v38
	v_fmac_f32_e32 v214, v39, v39
	v_fmac_f32_e32 v214, v40, v40
	v_fmac_f32_e32 v214, v41, v41
	v_fmac_f32_e32 v214, v42, v42
	v_fmac_f32_e32 v214, v43, v43
	v_fmac_f32_e32 v214, v44, v44
	v_fmac_f32_e32 v214, v45, v45
	v_fmac_f32_e32 v214, v46, v46
	v_fmac_f32_e32 v214, v47, v47
	s_waitcnt vmcnt(16)
	v_mul_f32_e32 v216, v48, v48
	v_fmac_f32_e32 v216, v49, v49
	v_fmac_f32_e32 v216, v50, v50
	v_fmac_f32_e32 v216, v51, v51
	v_fmac_f32_e32 v216, v52, v52
	v_fmac_f32_e32 v216, v53, v53
	v_fmac_f32_e32 v216, v54, v54
	v_fmac_f32_e32 v216, v55, v55
	v_fmac_f32_e32 v216, v56, v56
	v_fmac_f32_e32 v216, v57, v57
	v_fmac_f32_e32 v216, v58, v58
	v_fmac_f32_e32 v216, v59, v59
	v_fmac_f32_e32 v216, v60, v60
	v_fmac_f32_e32 v216, v61, v61
	v_fmac_f32_e32 v216, v62, v62
	v_fmac_f32_e32 v216, v63, v63
	s_waitcnt vmcnt(12)
	v_mul_f32_e32 v218, v64, v64
	v_fmac_f32_e32 v218, v65, v65
	v_fmac_f32_e32 v218, v66, v66
	v_fmac_f32_e32 v218, v67, v67
	v_fmac_f32_e32 v218, v68, v68
	v_fmac_f32_e32 v218, v69, v69
	v_fmac_f32_e32 v218, v70, v70
	v_fmac_f32_e32 v218, v71, v71
	v_fmac_f32_e32 v218, v72, v72
	v_fmac_f32_e32 v218, v73, v73
	v_fmac_f32_e32 v218, v74, v74
	v_fmac_f32_e32 v218, v75, v75
	v_fmac_f32_e32 v218, v76, v76
	v_fmac_f32_e32 v218, v77, v77
	v_fmac_f32_e32 v218, v78, v78
	v_fmac_f32_e32 v218, v79, v79
	s_waitcnt vmcnt(8)
	v_mul_f32_e32 v220, v80, v80
	v_fmac_f32_e32 v220, v81, v81
	v_fmac_f32_e32 v220, v82, v82
	v_fmac_f32_e32 v220, v83, v83
	v_fmac_f32_e32 v220, v84, v84
	v_fmac_f32_e32 v220, v85, v85
	v_fmac_f32_e32 v220, v86, v86
	v_fmac_f32_e32 v220, v87, v87
	v_fmac_f32_e32 v220, v88, v88
	v_fmac_f32_e32 v220, v89, v89
	v_fmac_f32_e32 v220, v90, v90
	v_fmac_f32_e32 v220, v91, v91
	v_fmac_f32_e32 v220, v92, v92
	v_fmac_f32_e32 v220, v93, v93
	v_fmac_f32_e32 v220, v94, v94
	v_fmac_f32_e32 v220, v95, v95
	s_waitcnt vmcnt(4)
	v_mul_f32_e32 v222, v134, v134
	v_fmac_f32_e32 v222, v135, v135
	v_fmac_f32_e32 v222, v136, v136
	v_fmac_f32_e32 v222, v137, v137
	v_fmac_f32_e32 v222, v138, v138
	v_fmac_f32_e32 v222, v139, v139
	v_fmac_f32_e32 v222, v140, v140
	v_fmac_f32_e32 v222, v141, v141
	v_fmac_f32_e32 v222, v142, v142
	v_fmac_f32_e32 v222, v143, v143
	v_fmac_f32_e32 v222, v144, v144
	v_fmac_f32_e32 v222, v145, v145
	v_fmac_f32_e32 v222, v146, v146
	v_fmac_f32_e32 v222, v147, v147
	v_fmac_f32_e32 v222, v148, v148
	v_fmac_f32_e32 v222, v149, v149
	s_waitcnt vmcnt(0)
	v_mul_f32_e32 v224, v150, v150
	v_fmac_f32_e32 v224, v151, v151
	v_fmac_f32_e32 v224, v152, v152
	v_fmac_f32_e32 v224, v153, v153
	v_fmac_f32_e32 v224, v154, v154
	v_fmac_f32_e32 v224, v155, v155
	v_fmac_f32_e32 v224, v156, v156
	v_fmac_f32_e32 v224, v157, v157
	v_fmac_f32_e32 v224, v158, v158
	v_fmac_f32_e32 v224, v159, v159
	v_fmac_f32_e32 v224, v160, v160
	v_fmac_f32_e32 v224, v161, v161
	v_fmac_f32_e32 v224, v162, v162
	v_fmac_f32_e32 v224, v163, v163
	v_fmac_f32_e32 v224, v164, v164
	v_fmac_f32_e32 v224, v165, v165
	ds_bpermute_b32 v211, v171, v210
	ds_bpermute_b32 v213, v171, v212
	ds_bpermute_b32 v215, v171, v214
	ds_bpermute_b32 v217, v171, v216
	ds_bpermute_b32 v219, v171, v218
	ds_bpermute_b32 v221, v171, v220
	ds_bpermute_b32 v223, v171, v222
	ds_bpermute_b32 v225, v171, v224
	s_waitcnt lgkmcnt(7)
	v_add_f32_e32 v210, v210, v211
	s_waitcnt lgkmcnt(6)
	v_add_f32_e32 v212, v212, v213
	s_waitcnt lgkmcnt(5)
	v_add_f32_e32 v214, v214, v215
	s_waitcnt lgkmcnt(4)
	v_add_f32_e32 v216, v216, v217
	s_waitcnt lgkmcnt(3)
	v_add_f32_e32 v218, v218, v219
	s_waitcnt lgkmcnt(2)
	v_add_f32_e32 v220, v220, v221
	s_waitcnt lgkmcnt(1)
	v_add_f32_e32 v222, v222, v223
	s_waitcnt lgkmcnt(0)
	v_add_f32_e32 v224, v224, v225
	ds_bpermute_b32 v211, v172, v210
	ds_bpermute_b32 v213, v172, v212
	ds_bpermute_b32 v215, v172, v214
	ds_bpermute_b32 v217, v172, v216
	ds_bpermute_b32 v219, v172, v218
	ds_bpermute_b32 v221, v172, v220
	ds_bpermute_b32 v223, v172, v222
	ds_bpermute_b32 v225, v172, v224
	s_waitcnt lgkmcnt(7)
	v_add_f32_e32 v210, v210, v211
	s_waitcnt lgkmcnt(6)
	v_add_f32_e32 v212, v212, v213
	s_waitcnt lgkmcnt(5)
	v_add_f32_e32 v214, v214, v215
	s_waitcnt lgkmcnt(4)
	v_add_f32_e32 v216, v216, v217
	s_waitcnt lgkmcnt(3)
	v_add_f32_e32 v218, v218, v219
	s_waitcnt lgkmcnt(2)
	v_add_f32_e32 v220, v220, v221
	s_waitcnt lgkmcnt(1)
	v_add_f32_e32 v222, v222, v223
	s_waitcnt lgkmcnt(0)
	v_add_f32_e32 v224, v224, v225
	ds_bpermute_b32 v211, v173, v210
	ds_bpermute_b32 v213, v173, v212
	ds_bpermute_b32 v215, v173, v214
	ds_bpermute_b32 v217, v173, v216
	ds_bpermute_b32 v219, v173, v218
	ds_bpermute_b32 v221, v173, v220
	ds_bpermute_b32 v223, v173, v222
	ds_bpermute_b32 v225, v173, v224
	s_waitcnt lgkmcnt(7)
	v_add_f32_e32 v210, v210, v211
	s_waitcnt lgkmcnt(6)
	v_add_f32_e32 v212, v212, v213
	s_waitcnt lgkmcnt(5)
	v_add_f32_e32 v214, v214, v215
	s_waitcnt lgkmcnt(4)
	v_add_f32_e32 v216, v216, v217
	s_waitcnt lgkmcnt(3)
	v_add_f32_e32 v218, v218, v219
	s_waitcnt lgkmcnt(2)
	v_add_f32_e32 v220, v220, v221
	s_waitcnt lgkmcnt(1)
	v_add_f32_e32 v222, v222, v223
	s_waitcnt lgkmcnt(0)
	v_add_f32_e32 v224, v224, v225
	ds_bpermute_b32 v211, v174, v210
	ds_bpermute_b32 v213, v174, v212
	ds_bpermute_b32 v215, v174, v214
	ds_bpermute_b32 v217, v174, v216
	ds_bpermute_b32 v219, v174, v218
	ds_bpermute_b32 v221, v174, v220
	ds_bpermute_b32 v223, v174, v222
	ds_bpermute_b32 v225, v174, v224
	s_waitcnt lgkmcnt(7)
	v_add_f32_e32 v210, v210, v211
	s_waitcnt lgkmcnt(6)
	v_add_f32_e32 v212, v212, v213
	s_waitcnt lgkmcnt(5)
	v_add_f32_e32 v214, v214, v215
	s_waitcnt lgkmcnt(4)
	v_add_f32_e32 v216, v216, v217
	s_waitcnt lgkmcnt(3)
	v_add_f32_e32 v218, v218, v219
	s_waitcnt lgkmcnt(2)
	v_add_f32_e32 v220, v220, v221
	s_waitcnt lgkmcnt(1)
	v_add_f32_e32 v222, v222, v223
	s_waitcnt lgkmcnt(0)
	v_add_f32_e32 v224, v224, v225
	ds_bpermute_b32 v211, v175, v210
	ds_bpermute_b32 v213, v175, v212
	ds_bpermute_b32 v215, v175, v214
	ds_bpermute_b32 v217, v175, v216
	ds_bpermute_b32 v219, v175, v218
	ds_bpermute_b32 v221, v175, v220
	ds_bpermute_b32 v223, v175, v222
	ds_bpermute_b32 v225, v175, v224
	s_waitcnt lgkmcnt(7)
	v_add_f32_e32 v210, v210, v211
	s_waitcnt lgkmcnt(6)
	v_add_f32_e32 v212, v212, v213
	s_waitcnt lgkmcnt(5)
	v_add_f32_e32 v214, v214, v215
	s_waitcnt lgkmcnt(4)
	v_add_f32_e32 v216, v216, v217
	s_waitcnt lgkmcnt(3)
	v_add_f32_e32 v218, v218, v219
	s_waitcnt lgkmcnt(2)
	v_add_f32_e32 v220, v220, v221
	s_waitcnt lgkmcnt(1)
	v_add_f32_e32 v222, v222, v223
	s_waitcnt lgkmcnt(0)
	v_add_f32_e32 v224, v224, v225
	ds_bpermute_b32 v211, v176, v210
	ds_bpermute_b32 v213, v176, v212
	ds_bpermute_b32 v215, v176, v214
	ds_bpermute_b32 v217, v176, v216
	ds_bpermute_b32 v219, v176, v218
	ds_bpermute_b32 v221, v176, v220
	ds_bpermute_b32 v223, v176, v222
	ds_bpermute_b32 v225, v176, v224
	s_waitcnt lgkmcnt(7)
	v_add_f32_e32 v210, v210, v211
	s_waitcnt lgkmcnt(6)
	v_add_f32_e32 v212, v212, v213
	s_waitcnt lgkmcnt(5)
	v_add_f32_e32 v214, v214, v215
	s_waitcnt lgkmcnt(4)
	v_add_f32_e32 v216, v216, v217
	s_waitcnt lgkmcnt(3)
	v_add_f32_e32 v218, v218, v219
	s_waitcnt lgkmcnt(2)
	v_add_f32_e32 v220, v220, v221
	s_waitcnt lgkmcnt(1)
	v_add_f32_e32 v222, v222, v223
	s_waitcnt lgkmcnt(0)
	v_add_f32_e32 v224, v224, v225
	v_fmamk_f32 v210, v210, 0x3a800000, v228
	v_fmamk_f32 v212, v212, 0x3a800000, v228
	v_fmamk_f32 v214, v214, 0x3a800000, v228
	v_fmamk_f32 v216, v216, 0x3a800000, v228
	v_fmamk_f32 v218, v218, 0x3a800000, v228
	v_fmamk_f32 v220, v220, 0x3a800000, v228
	v_fmamk_f32 v222, v222, 0x3a800000, v228
	v_fmamk_f32 v224, v224, 0x3a800000, v228
	v_rsq_f32_e32 v210, v210
	v_rsq_f32_e32 v212, v212
	v_rsq_f32_e32 v214, v214
	v_rsq_f32_e32 v216, v216
	v_rsq_f32_e32 v218, v218
	v_rsq_f32_e32 v220, v220
	v_rsq_f32_e32 v222, v222
	v_rsq_f32_e32 v224, v224
	v_pk_mul_f32 v[0:1], v[0:1], v[210:211] op_sel_hi:[1,0]
	v_pk_mul_f32 v[2:3], v[2:3], v[210:211] op_sel_hi:[1,0]
	v_pk_fma_f32 v[0:1], v[0:1], v[178:179], v[194:195]
	v_pk_fma_f32 v[2:3], v[2:3], v[180:181], v[196:197]
	v_cvt_pk_bf16_f32 v0, v0, v1
	v_cvt_pk_bf16_f32 v1, v2, v3
	global_store_dwordx2 v227, v[0:1], s[56:57] sc1
	v_pk_mul_f32 v[4:5], v[4:5], v[210:211] op_sel_hi:[1,0]
	v_pk_mul_f32 v[6:7], v[6:7], v[210:211] op_sel_hi:[1,0]
	v_pk_fma_f32 v[4:5], v[4:5], v[182:183], v[198:199]
	v_pk_fma_f32 v[6:7], v[6:7], v[184:185], v[200:201]
	v_cvt_pk_bf16_f32 v4, v4, v5
	v_cvt_pk_bf16_f32 v5, v6, v7
	global_store_dwordx2 v227, v[4:5], s[56:57] offset:512 sc1
	v_pk_mul_f32 v[8:9], v[8:9], v[210:211] op_sel_hi:[1,0]
	v_pk_mul_f32 v[10:11], v[10:11], v[210:211] op_sel_hi:[1,0]
	v_pk_fma_f32 v[8:9], v[8:9], v[186:187], v[202:203]
	v_pk_fma_f32 v[10:11], v[10:11], v[188:189], v[204:205]
	v_cvt_pk_bf16_f32 v8, v8, v9
	v_cvt_pk_bf16_f32 v9, v10, v11
	global_store_dwordx2 v227, v[8:9], s[56:57] offset:1024 sc1
	v_pk_mul_f32 v[12:13], v[12:13], v[210:211] op_sel_hi:[1,0]
	v_pk_mul_f32 v[14:15], v[14:15], v[210:211] op_sel_hi:[1,0]
	v_pk_fma_f32 v[12:13], v[12:13], v[190:191], v[206:207]
	v_pk_fma_f32 v[14:15], v[14:15], v[192:193], v[208:209]
	v_cvt_pk_bf16_f32 v12, v12, v13
	v_cvt_pk_bf16_f32 v13, v14, v15
	global_store_dwordx2 v227, v[12:13], s[56:57] offset:1536 sc1
	s_add_u32 s56, s56, 0x4000
	s_addc_u32 s57, s57, 0
	v_pk_mul_f32 v[16:17], v[16:17], v[212:213] op_sel_hi:[1,0]
	v_pk_mul_f32 v[18:19], v[18:19], v[212:213] op_sel_hi:[1,0]
	v_pk_fma_f32 v[16:17], v[16:17], v[178:179], v[194:195]
	v_pk_fma_f32 v[18:19], v[18:19], v[180:181], v[196:197]
	v_cvt_pk_bf16_f32 v16, v16, v17
	v_cvt_pk_bf16_f32 v17, v18, v19
	global_store_dwordx2 v227, v[16:17], s[56:57] sc1
	v_pk_mul_f32 v[20:21], v[20:21], v[212:213] op_sel_hi:[1,0]
	v_pk_mul_f32 v[22:23], v[22:23], v[212:213] op_sel_hi:[1,0]
	v_pk_fma_f32 v[20:21], v[20:21], v[182:183], v[198:199]
	v_pk_fma_f32 v[22:23], v[22:23], v[184:185], v[200:201]
	v_cvt_pk_bf16_f32 v20, v20, v21
	v_cvt_pk_bf16_f32 v21, v22, v23
	global_store_dwordx2 v227, v[20:21], s[56:57] offset:512 sc1
	v_pk_mul_f32 v[24:25], v[24:25], v[212:213] op_sel_hi:[1,0]
	v_pk_mul_f32 v[26:27], v[26:27], v[212:213] op_sel_hi:[1,0]
	v_pk_fma_f32 v[24:25], v[24:25], v[186:187], v[202:203]
	v_pk_fma_f32 v[26:27], v[26:27], v[188:189], v[204:205]
	v_cvt_pk_bf16_f32 v24, v24, v25
	v_cvt_pk_bf16_f32 v25, v26, v27
	global_store_dwordx2 v227, v[24:25], s[56:57] offset:1024 sc1
	v_pk_mul_f32 v[28:29], v[28:29], v[212:213] op_sel_hi:[1,0]
	v_pk_mul_f32 v[30:31], v[30:31], v[212:213] op_sel_hi:[1,0]
	v_pk_fma_f32 v[28:29], v[28:29], v[190:191], v[206:207]
	v_pk_fma_f32 v[30:31], v[30:31], v[192:193], v[208:209]
	v_cvt_pk_bf16_f32 v28, v28, v29
	v_cvt_pk_bf16_f32 v29, v30, v31
	global_store_dwordx2 v227, v[28:29], s[56:57] offset:1536 sc1
	s_add_u32 s56, s56, 0x4000
	s_addc_u32 s57, s57, 0
	v_pk_mul_f32 v[32:33], v[32:33], v[214:215] op_sel_hi:[1,0]
	v_pk_mul_f32 v[34:35], v[34:35], v[214:215] op_sel_hi:[1,0]
	v_pk_fma_f32 v[32:33], v[32:33], v[178:179], v[194:195]
	v_pk_fma_f32 v[34:35], v[34:35], v[180:181], v[196:197]
	v_cvt_pk_bf16_f32 v32, v32, v33
	v_cvt_pk_bf16_f32 v33, v34, v35
	global_store_dwordx2 v227, v[32:33], s[56:57] sc1
	v_pk_mul_f32 v[36:37], v[36:37], v[214:215] op_sel_hi:[1,0]
	v_pk_mul_f32 v[38:39], v[38:39], v[214:215] op_sel_hi:[1,0]
	v_pk_fma_f32 v[36:37], v[36:37], v[182:183], v[198:199]
	v_pk_fma_f32 v[38:39], v[38:39], v[184:185], v[200:201]
	v_cvt_pk_bf16_f32 v36, v36, v37
	v_cvt_pk_bf16_f32 v37, v38, v39
	global_store_dwordx2 v227, v[36:37], s[56:57] offset:512 sc1
	v_pk_mul_f32 v[40:41], v[40:41], v[214:215] op_sel_hi:[1,0]
	v_pk_mul_f32 v[42:43], v[42:43], v[214:215] op_sel_hi:[1,0]
	v_pk_fma_f32 v[40:41], v[40:41], v[186:187], v[202:203]
	v_pk_fma_f32 v[42:43], v[42:43], v[188:189], v[204:205]
	v_cvt_pk_bf16_f32 v40, v40, v41
	v_cvt_pk_bf16_f32 v41, v42, v43
	global_store_dwordx2 v227, v[40:41], s[56:57] offset:1024 sc1
	v_pk_mul_f32 v[44:45], v[44:45], v[214:215] op_sel_hi:[1,0]
	v_pk_mul_f32 v[46:47], v[46:47], v[214:215] op_sel_hi:[1,0]
	v_pk_fma_f32 v[44:45], v[44:45], v[190:191], v[206:207]
	v_pk_fma_f32 v[46:47], v[46:47], v[192:193], v[208:209]
	v_cvt_pk_bf16_f32 v44, v44, v45
	v_cvt_pk_bf16_f32 v45, v46, v47
	global_store_dwordx2 v227, v[44:45], s[56:57] offset:1536 sc1
	s_add_u32 s56, s56, 0x4000
	s_addc_u32 s57, s57, 0
	v_pk_mul_f32 v[48:49], v[48:49], v[216:217] op_sel_hi:[1,0]
	v_pk_mul_f32 v[50:51], v[50:51], v[216:217] op_sel_hi:[1,0]
	v_pk_fma_f32 v[48:49], v[48:49], v[178:179], v[194:195]
	v_pk_fma_f32 v[50:51], v[50:51], v[180:181], v[196:197]
	v_cvt_pk_bf16_f32 v48, v48, v49
	v_cvt_pk_bf16_f32 v49, v50, v51
	global_store_dwordx2 v227, v[48:49], s[56:57] sc1
	v_pk_mul_f32 v[52:53], v[52:53], v[216:217] op_sel_hi:[1,0]
	v_pk_mul_f32 v[54:55], v[54:55], v[216:217] op_sel_hi:[1,0]
	v_pk_fma_f32 v[52:53], v[52:53], v[182:183], v[198:199]
	v_pk_fma_f32 v[54:55], v[54:55], v[184:185], v[200:201]
	v_cvt_pk_bf16_f32 v52, v52, v53
	v_cvt_pk_bf16_f32 v53, v54, v55
	global_store_dwordx2 v227, v[52:53], s[56:57] offset:512 sc1
	v_pk_mul_f32 v[56:57], v[56:57], v[216:217] op_sel_hi:[1,0]
	v_pk_mul_f32 v[58:59], v[58:59], v[216:217] op_sel_hi:[1,0]
	v_pk_fma_f32 v[56:57], v[56:57], v[186:187], v[202:203]
	v_pk_fma_f32 v[58:59], v[58:59], v[188:189], v[204:205]
	v_cvt_pk_bf16_f32 v56, v56, v57
	v_cvt_pk_bf16_f32 v57, v58, v59
	global_store_dwordx2 v227, v[56:57], s[56:57] offset:1024 sc1
	v_pk_mul_f32 v[60:61], v[60:61], v[216:217] op_sel_hi:[1,0]
	v_pk_mul_f32 v[62:63], v[62:63], v[216:217] op_sel_hi:[1,0]
	v_pk_fma_f32 v[60:61], v[60:61], v[190:191], v[206:207]
	v_pk_fma_f32 v[62:63], v[62:63], v[192:193], v[208:209]
	v_cvt_pk_bf16_f32 v60, v60, v61
	v_cvt_pk_bf16_f32 v61, v62, v63
	global_store_dwordx2 v227, v[60:61], s[56:57] offset:1536 sc1
	s_add_u32 s56, s56, 0x4000
	s_addc_u32 s57, s57, 0
	v_pk_mul_f32 v[64:65], v[64:65], v[218:219] op_sel_hi:[1,0]
	v_pk_mul_f32 v[66:67], v[66:67], v[218:219] op_sel_hi:[1,0]
	v_pk_fma_f32 v[64:65], v[64:65], v[178:179], v[194:195]
	v_pk_fma_f32 v[66:67], v[66:67], v[180:181], v[196:197]
	v_cvt_pk_bf16_f32 v64, v64, v65
	v_cvt_pk_bf16_f32 v65, v66, v67
	global_store_dwordx2 v227, v[64:65], s[56:57] sc1
	v_pk_mul_f32 v[68:69], v[68:69], v[218:219] op_sel_hi:[1,0]
	v_pk_mul_f32 v[70:71], v[70:71], v[218:219] op_sel_hi:[1,0]
	v_pk_fma_f32 v[68:69], v[68:69], v[182:183], v[198:199]
	v_pk_fma_f32 v[70:71], v[70:71], v[184:185], v[200:201]
	v_cvt_pk_bf16_f32 v68, v68, v69
	v_cvt_pk_bf16_f32 v69, v70, v71
	global_store_dwordx2 v227, v[68:69], s[56:57] offset:512 sc1
	v_pk_mul_f32 v[72:73], v[72:73], v[218:219] op_sel_hi:[1,0]
	v_pk_mul_f32 v[74:75], v[74:75], v[218:219] op_sel_hi:[1,0]
	v_pk_fma_f32 v[72:73], v[72:73], v[186:187], v[202:203]
	v_pk_fma_f32 v[74:75], v[74:75], v[188:189], v[204:205]
	v_cvt_pk_bf16_f32 v72, v72, v73
	v_cvt_pk_bf16_f32 v73, v74, v75
	global_store_dwordx2 v227, v[72:73], s[56:57] offset:1024 sc1
	v_pk_mul_f32 v[76:77], v[76:77], v[218:219] op_sel_hi:[1,0]
	v_pk_mul_f32 v[78:79], v[78:79], v[218:219] op_sel_hi:[1,0]
	v_pk_fma_f32 v[76:77], v[76:77], v[190:191], v[206:207]
	v_pk_fma_f32 v[78:79], v[78:79], v[192:193], v[208:209]
	v_cvt_pk_bf16_f32 v76, v76, v77
	v_cvt_pk_bf16_f32 v77, v78, v79
	global_store_dwordx2 v227, v[76:77], s[56:57] offset:1536 sc1
	s_add_u32 s56, s56, 0x4000
	s_addc_u32 s57, s57, 0
	v_pk_mul_f32 v[80:81], v[80:81], v[220:221] op_sel_hi:[1,0]
	v_pk_mul_f32 v[82:83], v[82:83], v[220:221] op_sel_hi:[1,0]
	v_pk_fma_f32 v[80:81], v[80:81], v[178:179], v[194:195]
	v_pk_fma_f32 v[82:83], v[82:83], v[180:181], v[196:197]
	v_cvt_pk_bf16_f32 v80, v80, v81
	v_cvt_pk_bf16_f32 v81, v82, v83
	global_store_dwordx2 v227, v[80:81], s[56:57] sc1
	v_pk_mul_f32 v[84:85], v[84:85], v[220:221] op_sel_hi:[1,0]
	v_pk_mul_f32 v[86:87], v[86:87], v[220:221] op_sel_hi:[1,0]
	v_pk_fma_f32 v[84:85], v[84:85], v[182:183], v[198:199]
	v_pk_fma_f32 v[86:87], v[86:87], v[184:185], v[200:201]
	v_cvt_pk_bf16_f32 v84, v84, v85
	v_cvt_pk_bf16_f32 v85, v86, v87
	global_store_dwordx2 v227, v[84:85], s[56:57] offset:512 sc1
	v_pk_mul_f32 v[88:89], v[88:89], v[220:221] op_sel_hi:[1,0]
	v_pk_mul_f32 v[90:91], v[90:91], v[220:221] op_sel_hi:[1,0]
	v_pk_fma_f32 v[88:89], v[88:89], v[186:187], v[202:203]
	v_pk_fma_f32 v[90:91], v[90:91], v[188:189], v[204:205]
	v_cvt_pk_bf16_f32 v88, v88, v89
	v_cvt_pk_bf16_f32 v89, v90, v91
	global_store_dwordx2 v227, v[88:89], s[56:57] offset:1024 sc1
	v_pk_mul_f32 v[92:93], v[92:93], v[220:221] op_sel_hi:[1,0]
	v_pk_mul_f32 v[94:95], v[94:95], v[220:221] op_sel_hi:[1,0]
	v_pk_fma_f32 v[92:93], v[92:93], v[190:191], v[206:207]
	v_pk_fma_f32 v[94:95], v[94:95], v[192:193], v[208:209]
	v_cvt_pk_bf16_f32 v92, v92, v93
	v_cvt_pk_bf16_f32 v93, v94, v95
	global_store_dwordx2 v227, v[92:93], s[56:57] offset:1536 sc1
	s_add_u32 s56, s56, 0x4000
	s_addc_u32 s57, s57, 0
	v_pk_mul_f32 v[134:135], v[134:135], v[222:223] op_sel_hi:[1,0]
	v_pk_mul_f32 v[136:137], v[136:137], v[222:223] op_sel_hi:[1,0]
	v_pk_fma_f32 v[134:135], v[134:135], v[178:179], v[194:195]
	v_pk_fma_f32 v[136:137], v[136:137], v[180:181], v[196:197]
	v_cvt_pk_bf16_f32 v134, v134, v135
	v_cvt_pk_bf16_f32 v135, v136, v137
	global_store_dwordx2 v227, v[134:135], s[56:57] sc1
	v_pk_mul_f32 v[138:139], v[138:139], v[222:223] op_sel_hi:[1,0]
	v_pk_mul_f32 v[140:141], v[140:141], v[222:223] op_sel_hi:[1,0]
	v_pk_fma_f32 v[138:139], v[138:139], v[182:183], v[198:199]
	v_pk_fma_f32 v[140:141], v[140:141], v[184:185], v[200:201]
	v_cvt_pk_bf16_f32 v138, v138, v139
	v_cvt_pk_bf16_f32 v139, v140, v141
	global_store_dwordx2 v227, v[138:139], s[56:57] offset:512 sc1
	v_pk_mul_f32 v[142:143], v[142:143], v[222:223] op_sel_hi:[1,0]
	v_pk_mul_f32 v[144:145], v[144:145], v[222:223] op_sel_hi:[1,0]
	v_pk_fma_f32 v[142:143], v[142:143], v[186:187], v[202:203]
	v_pk_fma_f32 v[144:145], v[144:145], v[188:189], v[204:205]
	v_cvt_pk_bf16_f32 v142, v142, v143
	v_cvt_pk_bf16_f32 v143, v144, v145
	global_store_dwordx2 v227, v[142:143], s[56:57] offset:1024 sc1
	v_pk_mul_f32 v[146:147], v[146:147], v[222:223] op_sel_hi:[1,0]
	v_pk_mul_f32 v[148:149], v[148:149], v[222:223] op_sel_hi:[1,0]
	v_pk_fma_f32 v[146:147], v[146:147], v[190:191], v[206:207]
	v_pk_fma_f32 v[148:149], v[148:149], v[192:193], v[208:209]
	v_cvt_pk_bf16_f32 v146, v146, v147
	v_cvt_pk_bf16_f32 v147, v148, v149
	global_store_dwordx2 v227, v[146:147], s[56:57] offset:1536 sc1
	s_add_u32 s56, s56, 0x4000
	s_addc_u32 s57, s57, 0
	v_pk_mul_f32 v[150:151], v[150:151], v[224:225] op_sel_hi:[1,0]
	v_pk_mul_f32 v[152:153], v[152:153], v[224:225] op_sel_hi:[1,0]
	v_pk_fma_f32 v[150:151], v[150:151], v[178:179], v[194:195]
	v_pk_fma_f32 v[152:153], v[152:153], v[180:181], v[196:197]
	v_cvt_pk_bf16_f32 v150, v150, v151
	v_cvt_pk_bf16_f32 v151, v152, v153
	global_store_dwordx2 v227, v[150:151], s[56:57] sc1
	v_pk_mul_f32 v[154:155], v[154:155], v[224:225] op_sel_hi:[1,0]
	v_pk_mul_f32 v[156:157], v[156:157], v[224:225] op_sel_hi:[1,0]
	v_pk_fma_f32 v[154:155], v[154:155], v[182:183], v[198:199]
	v_pk_fma_f32 v[156:157], v[156:157], v[184:185], v[200:201]
	v_cvt_pk_bf16_f32 v154, v154, v155
	v_cvt_pk_bf16_f32 v155, v156, v157
	global_store_dwordx2 v227, v[154:155], s[56:57] offset:512 sc1
	v_pk_mul_f32 v[158:159], v[158:159], v[224:225] op_sel_hi:[1,0]
	v_pk_mul_f32 v[160:161], v[160:161], v[224:225] op_sel_hi:[1,0]
	v_pk_fma_f32 v[158:159], v[158:159], v[186:187], v[202:203]
	v_pk_fma_f32 v[160:161], v[160:161], v[188:189], v[204:205]
	v_cvt_pk_bf16_f32 v158, v158, v159
	v_cvt_pk_bf16_f32 v159, v160, v161
	global_store_dwordx2 v227, v[158:159], s[56:57] offset:1024 sc1
	v_pk_mul_f32 v[162:163], v[162:163], v[224:225] op_sel_hi:[1,0]
	v_pk_mul_f32 v[164:165], v[164:165], v[224:225] op_sel_hi:[1,0]
	v_pk_fma_f32 v[162:163], v[162:163], v[190:191], v[206:207]
	v_pk_fma_f32 v[164:165], v[164:165], v[192:193], v[208:209]
	v_cvt_pk_bf16_f32 v162, v162, v163
	v_cvt_pk_bf16_f32 v163, v164, v165
	global_store_dwordx2 v227, v[162:163], s[56:57] offset:1536 sc1
